# PEER back-edge reissue in groups of 2 experts instead of 4 (variant of v66)
# speedup vs baseline: 1.0071x; 1.0071x over previous
.LBB0_918:
	s_andn2_saveexec_b64 s[50:51], s[50:51]
	v_mul_f32_e32 v34, v33, v33
	v_fmamk_f32 v35, v34, 0xba1345e1, v139
	v_fmaak_f32 v35, v34, v35, 0xbcdac9b8
	v_fmaak_f32 v35, v34, v35, 0x3de703be
	v_fmaak_f32 v35, v34, v35, 0xbec09330
	v_fmaak_f32 v34, v34, v35, 0x3e0375d0
	v_fma_f32 v34, |v33|, v34, |v33|
	s_or_b64 exec, exec, s[50:51]
	v_cvt_scalef32_pk_f32_fp4 v[36:37], v204, 1.0
	v_pk_fma_f32 v[36:37], s[30:31], v[36:37], v[200:201] op_sel_hi:[0,1,1]
	v_cvt_scalef32_pk_f32_fp4 v[38:39], v204, 1.0 op_sel:[1,0,0]
	v_cvt_scalef32_pk_f32_fp4 v[52:53], v202, 1.0
	v_pk_fma_f32 v[38:39], s[30:31], v[38:39], v[218:219] op_sel_hi:[0,1,1]
	v_cvt_scalef32_pk_f32_fp4 v[40:41], v204, 1.0 op_sel:[0,1,0]
	v_pk_fma_f32 v[36:37], s[28:29], v[52:53], v[36:37] op_sel_hi:[0,1,1]
	v_cvt_scalef32_pk_f32_fp4 v[52:53], v202, 1.0 op_sel:[1,0,0]
	v_pk_fma_f32 v[40:41], s[30:31], v[40:41], v[216:217] op_sel_hi:[0,1,1]
	v_cvt_scalef32_pk_f32_fp4 v[42:43], v204, 1.0 op_sel:[1,1,0]
	v_pk_fma_f32 v[38:39], s[28:29], v[52:53], v[38:39] op_sel_hi:[0,1,1]
	v_cvt_scalef32_pk_f32_fp4 v[52:53], v202, 1.0 op_sel:[0,1,0]
	v_pk_fma_f32 v[42:43], s[30:31], v[42:43], v[214:215] op_sel_hi:[0,1,1]
	v_cvt_scalef32_pk_f32_fp4 v[44:45], v205, 1.0
	v_pk_fma_f32 v[40:41], s[28:29], v[52:53], v[40:41] op_sel_hi:[0,1,1]
	v_cvt_scalef32_pk_f32_fp4 v[52:53], v202, 1.0 op_sel:[1,1,0]
	v_pk_fma_f32 v[44:45], s[30:31], v[44:45], v[212:213] op_sel_hi:[0,1,1]
	v_cvt_scalef32_pk_f32_fp4 v[46:47], v205, 1.0 op_sel:[1,0,0]
	v_pk_fma_f32 v[42:43], s[28:29], v[52:53], v[42:43] op_sel_hi:[0,1,1]
	v_cvt_scalef32_pk_f32_fp4 v[52:53], v203, 1.0
	v_pk_fma_f32 v[46:47], s[30:31], v[46:47], v[210:211] op_sel_hi:[0,1,1]
	v_cvt_scalef32_pk_f32_fp4 v[48:49], v205, 1.0 op_sel:[0,1,0]
	v_pk_fma_f32 v[44:45], s[28:29], v[52:53], v[44:45] op_sel_hi:[0,1,1]
	v_cvt_scalef32_pk_f32_fp4 v[52:53], v203, 1.0 op_sel:[1,0,0]
	v_pk_fma_f32 v[48:49], s[30:31], v[48:49], v[208:209] op_sel_hi:[0,1,1]
	v_cvt_scalef32_pk_f32_fp4 v[50:51], v205, 1.0 op_sel:[1,1,0]
	v_pk_fma_f32 v[46:47], s[28:29], v[52:53], v[46:47] op_sel_hi:[0,1,1]
	v_cvt_scalef32_pk_f32_fp4 v[52:53], v203, 1.0 op_sel:[0,1,0]
	v_pk_fma_f32 v[50:51], s[30:31], v[50:51], v[206:207] op_sel_hi:[0,1,1]
	v_pk_fma_f32 v[48:49], s[28:29], v[52:53], v[48:49] op_sel_hi:[0,1,1]
	v_cvt_scalef32_pk_f32_fp4 v[52:53], v203, 1.0 op_sel:[1,1,0]
	v_pk_fma_f32 v[50:51], s[28:29], v[52:53], v[50:51] op_sel_hi:[0,1,1]
	v_cvt_scalef32_pk_f32_fp4 v[52:53], v198, 1.0
	v_pk_fma_f32 v[36:37], s[26:27], v[52:53], v[36:37] op_sel_hi:[0,1,1]
	v_cvt_scalef32_pk_f32_fp4 v[52:53], v198, 1.0 op_sel:[1,0,0]
	v_pk_fma_f32 v[38:39], s[26:27], v[52:53], v[38:39] op_sel_hi:[0,1,1]
	v_cvt_scalef32_pk_f32_fp4 v[52:53], v198, 1.0 op_sel:[0,1,0]
	v_pk_fma_f32 v[40:41], s[26:27], v[52:53], v[40:41] op_sel_hi:[0,1,1]
	v_cvt_scalef32_pk_f32_fp4 v[52:53], v198, 1.0 op_sel:[1,1,0]
	v_pk_fma_f32 v[42:43], s[26:27], v[52:53], v[42:43] op_sel_hi:[0,1,1]
	v_cvt_scalef32_pk_f32_fp4 v[52:53], v199, 1.0
	v_pk_fma_f32 v[44:45], s[26:27], v[52:53], v[44:45] op_sel_hi:[0,1,1]
	v_cvt_scalef32_pk_f32_fp4 v[52:53], v199, 1.0 op_sel:[1,0,0]
	v_pk_fma_f32 v[46:47], s[26:27], v[52:53], v[46:47] op_sel_hi:[0,1,1]
	v_cvt_scalef32_pk_f32_fp4 v[52:53], v199, 1.0 op_sel:[0,1,0]
	v_pk_fma_f32 v[48:49], s[26:27], v[52:53], v[48:49] op_sel_hi:[0,1,1]
	v_cvt_scalef32_pk_f32_fp4 v[52:53], v199, 1.0 op_sel:[1,1,0]
	v_pk_fma_f32 v[50:51], s[26:27], v[52:53], v[50:51] op_sel_hi:[0,1,1]
	v_cvt_scalef32_pk_f32_fp4 v[52:53], v196, 1.0
	v_pk_fma_f32 v[36:37], s[10:11], v[52:53], v[36:37] op_sel_hi:[0,1,1]
	v_cvt_scalef32_pk_f32_fp4 v[52:53], v196, 1.0 op_sel:[1,0,0]
	v_pk_fma_f32 v[38:39], s[10:11], v[52:53], v[38:39] op_sel_hi:[0,1,1]
	v_cvt_scalef32_pk_f32_fp4 v[52:53], v196, 1.0 op_sel:[0,1,0]
	v_pk_fma_f32 v[40:41], s[10:11], v[52:53], v[40:41] op_sel_hi:[0,1,1]
	v_cvt_scalef32_pk_f32_fp4 v[52:53], v196, 1.0 op_sel:[1,1,0]
	v_pk_fma_f32 v[42:43], s[10:11], v[52:53], v[42:43] op_sel_hi:[0,1,1]
	v_cvt_scalef32_pk_f32_fp4 v[52:53], v197, 1.0
	v_pk_fma_f32 v[44:45], s[10:11], v[52:53], v[44:45] op_sel_hi:[0,1,1]
	v_cvt_scalef32_pk_f32_fp4 v[52:53], v197, 1.0 op_sel:[1,0,0]
	v_pk_fma_f32 v[46:47], s[10:11], v[52:53], v[46:47] op_sel_hi:[0,1,1]
	v_cvt_scalef32_pk_f32_fp4 v[52:53], v197, 1.0 op_sel:[0,1,0]
	v_pk_fma_f32 v[48:49], s[10:11], v[52:53], v[48:49] op_sel_hi:[0,1,1]
	v_cvt_scalef32_pk_f32_fp4 v[52:53], v197, 1.0 op_sel:[1,1,0]
	v_pk_fma_f32 v[50:51], s[10:11], v[52:53], v[50:51] op_sel_hi:[0,1,1]
	v_cvt_scalef32_pk_f32_fp4 v[52:53], v194, 1.0
	v_pk_fma_f32 v[36:37], s[40:41], v[52:53], v[36:37] op_sel_hi:[0,1,1]
	v_cvt_scalef32_pk_f32_fp4 v[52:53], v194, 1.0 op_sel:[1,0,0]
	v_pk_fma_f32 v[38:39], s[40:41], v[52:53], v[38:39] op_sel_hi:[0,1,1]
	v_cvt_scalef32_pk_f32_fp4 v[52:53], v194, 1.0 op_sel:[0,1,0]
	v_pk_fma_f32 v[40:41], s[40:41], v[52:53], v[40:41] op_sel_hi:[0,1,1]
	v_cvt_scalef32_pk_f32_fp4 v[52:53], v194, 1.0 op_sel:[1,1,0]
	v_pk_fma_f32 v[42:43], s[40:41], v[52:53], v[42:43] op_sel_hi:[0,1,1]
	v_cvt_scalef32_pk_f32_fp4 v[52:53], v195, 1.0
	v_pk_fma_f32 v[44:45], s[40:41], v[52:53], v[44:45] op_sel_hi:[0,1,1]
	v_cvt_scalef32_pk_f32_fp4 v[52:53], v195, 1.0 op_sel:[1,0,0]
	v_pk_fma_f32 v[46:47], s[40:41], v[52:53], v[46:47] op_sel_hi:[0,1,1]
	v_cvt_scalef32_pk_f32_fp4 v[52:53], v195, 1.0 op_sel:[0,1,0]
	v_pk_fma_f32 v[48:49], s[40:41], v[52:53], v[48:49] op_sel_hi:[0,1,1]
	v_cvt_scalef32_pk_f32_fp4 v[52:53], v195, 1.0 op_sel:[1,1,0]
	v_pk_fma_f32 v[50:51], s[40:41], v[52:53], v[50:51] op_sel_hi:[0,1,1]
	v_cvt_scalef32_pk_f32_fp4 v[52:53], v192, 1.0
	v_pk_fma_f32 v[36:37], s[38:39], v[52:53], v[36:37] op_sel_hi:[0,1,1]
	v_cvt_scalef32_pk_f32_fp4 v[52:53], v192, 1.0 op_sel:[1,0,0]
	v_pk_fma_f32 v[38:39], s[38:39], v[52:53], v[38:39] op_sel_hi:[0,1,1]
	v_cvt_scalef32_pk_f32_fp4 v[52:53], v192, 1.0 op_sel:[0,1,0]
	v_pk_fma_f32 v[40:41], s[38:39], v[52:53], v[40:41] op_sel_hi:[0,1,1]
	v_cvt_scalef32_pk_f32_fp4 v[52:53], v192, 1.0 op_sel:[1,1,0]
	v_pk_fma_f32 v[42:43], s[38:39], v[52:53], v[42:43] op_sel_hi:[0,1,1]
	v_cvt_scalef32_pk_f32_fp4 v[52:53], v193, 1.0
	v_pk_fma_f32 v[44:45], s[38:39], v[52:53], v[44:45] op_sel_hi:[0,1,1]
	v_cvt_scalef32_pk_f32_fp4 v[52:53], v193, 1.0 op_sel:[1,0,0]
	v_pk_fma_f32 v[46:47], s[38:39], v[52:53], v[46:47] op_sel_hi:[0,1,1]
	v_cvt_scalef32_pk_f32_fp4 v[52:53], v193, 1.0 op_sel:[0,1,0]
	v_pk_fma_f32 v[48:49], s[38:39], v[52:53], v[48:49] op_sel_hi:[0,1,1]
	v_cvt_scalef32_pk_f32_fp4 v[52:53], v193, 1.0 op_sel:[1,1,0]
	v_pk_fma_f32 v[50:51], s[38:39], v[52:53], v[50:51] op_sel_hi:[0,1,1]
	v_cvt_scalef32_pk_f32_fp4 v[52:53], v190, 1.0
	v_pk_fma_f32 v[36:37], s[36:37], v[52:53], v[36:37] op_sel_hi:[0,1,1]
	v_cvt_scalef32_pk_f32_fp4 v[52:53], v190, 1.0 op_sel:[1,0,0]
	v_pk_fma_f32 v[38:39], s[36:37], v[52:53], v[38:39] op_sel_hi:[0,1,1]
	v_cvt_scalef32_pk_f32_fp4 v[52:53], v190, 1.0 op_sel:[0,1,0]
	v_pk_fma_f32 v[40:41], s[36:37], v[52:53], v[40:41] op_sel_hi:[0,1,1]
	v_cvt_scalef32_pk_f32_fp4 v[52:53], v190, 1.0 op_sel:[1,1,0]
	v_pk_fma_f32 v[42:43], s[36:37], v[52:53], v[42:43] op_sel_hi:[0,1,1]
	v_cvt_scalef32_pk_f32_fp4 v[52:53], v191, 1.0
	v_pk_fma_f32 v[44:45], s[36:37], v[52:53], v[44:45] op_sel_hi:[0,1,1]
	v_cvt_scalef32_pk_f32_fp4 v[52:53], v191, 1.0 op_sel:[1,0,0]
	v_pk_fma_f32 v[46:47], s[36:37], v[52:53], v[46:47] op_sel_hi:[0,1,1]
	v_cvt_scalef32_pk_f32_fp4 v[52:53], v191, 1.0 op_sel:[0,1,0]
	v_pk_fma_f32 v[48:49], s[36:37], v[52:53], v[48:49] op_sel_hi:[0,1,1]
	v_cvt_scalef32_pk_f32_fp4 v[52:53], v191, 1.0 op_sel:[1,1,0]
	v_pk_fma_f32 v[50:51], s[36:37], v[52:53], v[50:51] op_sel_hi:[0,1,1]
	v_cvt_scalef32_pk_f32_fp4 v[52:53], v188, 1.0
	v_pk_fma_f32 v[36:37], s[34:35], v[52:53], v[36:37] op_sel_hi:[0,1,1]
	v_cvt_scalef32_pk_f32_fp4 v[52:53], v188, 1.0 op_sel:[1,0,0]
	v_pk_fma_f32 v[38:39], s[34:35], v[52:53], v[38:39] op_sel_hi:[0,1,1]
	v_cvt_scalef32_pk_f32_fp4 v[52:53], v188, 1.0 op_sel:[0,1,0]
	v_pk_fma_f32 v[40:41], s[34:35], v[52:53], v[40:41] op_sel_hi:[0,1,1]
	v_cvt_scalef32_pk_f32_fp4 v[52:53], v188, 1.0 op_sel:[1,1,0]
	v_pk_fma_f32 v[42:43], s[34:35], v[52:53], v[42:43] op_sel_hi:[0,1,1]
	v_cvt_scalef32_pk_f32_fp4 v[52:53], v189, 1.0
	v_pk_fma_f32 v[44:45], s[34:35], v[52:53], v[44:45] op_sel_hi:[0,1,1]
	v_cvt_scalef32_pk_f32_fp4 v[52:53], v189, 1.0 op_sel:[1,0,0]
	v_pk_fma_f32 v[46:47], s[34:35], v[52:53], v[46:47] op_sel_hi:[0,1,1]
	v_cvt_scalef32_pk_f32_fp4 v[52:53], v189, 1.0 op_sel:[0,1,0]
	v_pk_fma_f32 v[48:49], s[34:35], v[52:53], v[48:49] op_sel_hi:[0,1,1]
	v_cvt_scalef32_pk_f32_fp4 v[52:53], v189, 1.0 op_sel:[1,1,0]
	v_pk_fma_f32 v[50:51], s[34:35], v[52:53], v[50:51] op_sel_hi:[0,1,1]
	v_cvt_scalef32_pk_f32_fp4 v[52:53], v186, 1.0
	v_pk_fma_f32 v[36:37], s[48:49], v[52:53], v[36:37] op_sel_hi:[0,1,1]
	v_cvt_scalef32_pk_f32_fp4 v[52:53], v186, 1.0 op_sel:[1,0,0]
	v_pk_fma_f32 v[38:39], s[48:49], v[52:53], v[38:39] op_sel_hi:[0,1,1]
	v_cvt_scalef32_pk_f32_fp4 v[52:53], v186, 1.0 op_sel:[0,1,0]
	v_pk_fma_f32 v[40:41], s[48:49], v[52:53], v[40:41] op_sel_hi:[0,1,1]
	v_cvt_scalef32_pk_f32_fp4 v[52:53], v186, 1.0 op_sel:[1,1,0]
	v_pk_fma_f32 v[42:43], s[48:49], v[52:53], v[42:43] op_sel_hi:[0,1,1]
	v_cvt_scalef32_pk_f32_fp4 v[52:53], v187, 1.0
	v_pk_fma_f32 v[44:45], s[48:49], v[52:53], v[44:45] op_sel_hi:[0,1,1]
	v_cvt_scalef32_pk_f32_fp4 v[52:53], v187, 1.0 op_sel:[1,0,0]
	v_pk_fma_f32 v[46:47], s[48:49], v[52:53], v[46:47] op_sel_hi:[0,1,1]
	v_cvt_scalef32_pk_f32_fp4 v[52:53], v187, 1.0 op_sel:[0,1,0]
	v_pk_fma_f32 v[48:49], s[48:49], v[52:53], v[48:49] op_sel_hi:[0,1,1]
	v_cvt_scalef32_pk_f32_fp4 v[52:53], v187, 1.0 op_sel:[1,1,0]
	v_pk_fma_f32 v[50:51], s[48:49], v[52:53], v[50:51] op_sel_hi:[0,1,1]
	v_cvt_scalef32_pk_f32_fp4 v[52:53], v184, 1.0
	v_pk_fma_f32 v[36:37], s[46:47], v[52:53], v[36:37] op_sel_hi:[0,1,1]
	v_cvt_scalef32_pk_f32_fp4 v[52:53], v184, 1.0 op_sel:[1,0,0]
	v_pk_fma_f32 v[38:39], s[46:47], v[52:53], v[38:39] op_sel_hi:[0,1,1]
	v_cvt_scalef32_pk_f32_fp4 v[52:53], v184, 1.0 op_sel:[0,1,0]
	v_pk_fma_f32 v[40:41], s[46:47], v[52:53], v[40:41] op_sel_hi:[0,1,1]
	v_cvt_scalef32_pk_f32_fp4 v[52:53], v184, 1.0 op_sel:[1,1,0]
	v_pk_fma_f32 v[42:43], s[46:47], v[52:53], v[42:43] op_sel_hi:[0,1,1]
	v_cvt_scalef32_pk_f32_fp4 v[52:53], v185, 1.0
	v_pk_fma_f32 v[44:45], s[46:47], v[52:53], v[44:45] op_sel_hi:[0,1,1]
	v_cvt_scalef32_pk_f32_fp4 v[52:53], v185, 1.0 op_sel:[1,0,0]
	v_pk_fma_f32 v[46:47], s[46:47], v[52:53], v[46:47] op_sel_hi:[0,1,1]
	v_cvt_scalef32_pk_f32_fp4 v[52:53], v185, 1.0 op_sel:[0,1,0]
	v_pk_fma_f32 v[48:49], s[46:47], v[52:53], v[48:49] op_sel_hi:[0,1,1]
	v_cvt_scalef32_pk_f32_fp4 v[52:53], v185, 1.0 op_sel:[1,1,0]
	v_pk_fma_f32 v[50:51], s[46:47], v[52:53], v[50:51] op_sel_hi:[0,1,1]
	v_cvt_scalef32_pk_f32_fp4 v[52:53], v182, 1.0
	v_pk_fma_f32 v[36:37], s[44:45], v[52:53], v[36:37] op_sel_hi:[0,1,1]
	v_cvt_scalef32_pk_f32_fp4 v[52:53], v182, 1.0 op_sel:[1,0,0]
	v_pk_fma_f32 v[38:39], s[44:45], v[52:53], v[38:39] op_sel_hi:[0,1,1]
	v_cvt_scalef32_pk_f32_fp4 v[52:53], v182, 1.0 op_sel:[0,1,0]
	v_pk_fma_f32 v[40:41], s[44:45], v[52:53], v[40:41] op_sel_hi:[0,1,1]
	v_cvt_scalef32_pk_f32_fp4 v[52:53], v182, 1.0 op_sel:[1,1,0]
	v_pk_fma_f32 v[42:43], s[44:45], v[52:53], v[42:43] op_sel_hi:[0,1,1]
	v_cvt_scalef32_pk_f32_fp4 v[52:53], v183, 1.0
	v_pk_fma_f32 v[44:45], s[44:45], v[52:53], v[44:45] op_sel_hi:[0,1,1]
	v_cvt_scalef32_pk_f32_fp4 v[52:53], v183, 1.0 op_sel:[1,0,0]
	v_pk_fma_f32 v[46:47], s[44:45], v[52:53], v[46:47] op_sel_hi:[0,1,1]
	v_cvt_scalef32_pk_f32_fp4 v[52:53], v183, 1.0 op_sel:[0,1,0]
	v_pk_fma_f32 v[48:49], s[44:45], v[52:53], v[48:49] op_sel_hi:[0,1,1]
	v_cvt_scalef32_pk_f32_fp4 v[52:53], v183, 1.0 op_sel:[1,1,0]
	v_pk_fma_f32 v[50:51], s[44:45], v[52:53], v[50:51] op_sel_hi:[0,1,1]
	v_cvt_scalef32_pk_f32_fp4 v[52:53], v180, 1.0
	v_pk_fma_f32 v[36:37], s[42:43], v[52:53], v[36:37] op_sel_hi:[0,1,1]
	v_cvt_scalef32_pk_f32_fp4 v[52:53], v180, 1.0 op_sel:[1,0,0]
	v_pk_fma_f32 v[38:39], s[42:43], v[52:53], v[38:39] op_sel_hi:[0,1,1]
	v_cvt_scalef32_pk_f32_fp4 v[52:53], v180, 1.0 op_sel:[0,1,0]
	v_pk_fma_f32 v[40:41], s[42:43], v[52:53], v[40:41] op_sel_hi:[0,1,1]
	v_cvt_scalef32_pk_f32_fp4 v[52:53], v180, 1.0 op_sel:[1,1,0]
	v_pk_fma_f32 v[42:43], s[42:43], v[52:53], v[42:43] op_sel_hi:[0,1,1]
	v_cvt_scalef32_pk_f32_fp4 v[52:53], v181, 1.0
	v_pk_fma_f32 v[44:45], s[42:43], v[52:53], v[44:45] op_sel_hi:[0,1,1]
	v_cvt_scalef32_pk_f32_fp4 v[52:53], v181, 1.0 op_sel:[1,0,0]
	v_pk_fma_f32 v[46:47], s[42:43], v[52:53], v[46:47] op_sel_hi:[0,1,1]
	v_cvt_scalef32_pk_f32_fp4 v[52:53], v181, 1.0 op_sel:[0,1,0]
	v_pk_fma_f32 v[48:49], s[42:43], v[52:53], v[48:49] op_sel_hi:[0,1,1]
	v_cvt_scalef32_pk_f32_fp4 v[52:53], v181, 1.0 op_sel:[1,1,0]
	v_pk_fma_f32 v[50:51], s[42:43], v[52:53], v[50:51] op_sel_hi:[0,1,1]
	v_mov_b32_e32 v35, s59
	v_mov_b32_e32 v52, s35
	v_cndmask_b32_e64 v35, v35, v52, s[8:9]
	v_mov_b32_e32 v52, s43
	v_bfi_b32 v33, s55, v34, v33
	v_cndmask_b32_e64 v35, v35, v52, s[6:7]
	v_mov_b32_e32 v52, s11
	v_mul_f32_e32 v32, 0.5, v32
	v_add_f32_e32 v33, 1.0, v33
	v_cndmask_b32_e64 v35, v35, v52, s[4:5]
	v_mul_f32_e32 v32, v32, v33
	v_mul_f32_e32 v32, v35, v32
	v_cvt_scalef32_pk_f32_fp4 v[34:35], v178, 1.0 op_sel:[1,0,0]
	v_readlane_b32 s10, v32, 0
	v_readlane_b32 s26, v32, 32
	v_readlane_b32 s28, v32, 16
	v_readlane_b32 s30, v32, 48
	v_cvt_scalef32_pk_f32_fp4 v[32:33], v178, 1.0
	v_pk_fma_f32 v[32:33], s[10:11], v[32:33], v[36:37] op_sel_hi:[0,1,1]
	v_cvt_scalef32_pk_f32_fp4 v[36:37], v178, 1.0 op_sel:[0,1,0]
	v_pk_fma_f32 v[36:37], s[10:11], v[36:37], v[40:41] op_sel_hi:[0,1,1]
	v_cvt_scalef32_pk_f32_fp4 v[40:41], v179, 1.0
	v_pk_fma_f32 v[40:41], s[10:11], v[40:41], v[44:45] op_sel_hi:[0,1,1]
	v_cvt_scalef32_pk_f32_fp4 v[44:45], v179, 1.0 op_sel:[0,1,0]
	v_pk_fma_f32 v[44:45], s[10:11], v[44:45], v[48:49] op_sel_hi:[0,1,1]
	v_cvt_scalef32_pk_f32_fp4 v[48:49], v176, 1.0
	v_pk_fma_f32 v[34:35], s[10:11], v[34:35], v[38:39] op_sel_hi:[0,1,1]
	v_pk_fma_f32 v[32:33], s[26:27], v[48:49], v[32:33] op_sel_hi:[0,1,1]
	v_cvt_scalef32_pk_f32_fp4 v[48:49], v176, 1.0 op_sel:[1,0,0]
	v_cvt_scalef32_pk_f32_fp4 v[38:39], v178, 1.0 op_sel:[1,1,0]
	v_pk_fma_f32 v[34:35], s[26:27], v[48:49], v[34:35] op_sel_hi:[0,1,1]
	v_cvt_scalef32_pk_f32_fp4 v[48:49], v176, 1.0 op_sel:[0,1,0]
	v_pk_fma_f32 v[38:39], s[10:11], v[38:39], v[42:43] op_sel_hi:[0,1,1]
	v_pk_fma_f32 v[36:37], s[26:27], v[48:49], v[36:37] op_sel_hi:[0,1,1]
	v_cvt_scalef32_pk_f32_fp4 v[48:49], v176, 1.0 op_sel:[1,1,0]
	v_cvt_scalef32_pk_f32_fp4 v[42:43], v179, 1.0 op_sel:[1,0,0]
	v_pk_fma_f32 v[38:39], s[26:27], v[48:49], v[38:39] op_sel_hi:[0,1,1]
	v_cvt_scalef32_pk_f32_fp4 v[48:49], v177, 1.0
	v_pk_fma_f32 v[42:43], s[10:11], v[42:43], v[46:47] op_sel_hi:[0,1,1]
	v_pk_fma_f32 v[40:41], s[26:27], v[48:49], v[40:41] op_sel_hi:[0,1,1]
	v_cvt_scalef32_pk_f32_fp4 v[48:49], v177, 1.0 op_sel:[1,0,0]
	v_cvt_scalef32_pk_f32_fp4 v[46:47], v179, 1.0 op_sel:[1,1,0]
	v_pk_fma_f32 v[42:43], s[26:27], v[48:49], v[42:43] op_sel_hi:[0,1,1]
	v_cvt_scalef32_pk_f32_fp4 v[48:49], v177, 1.0 op_sel:[0,1,0]
	v_pk_fma_f32 v[46:47], s[10:11], v[46:47], v[50:51] op_sel_hi:[0,1,1]
	v_pk_fma_f32 v[44:45], s[26:27], v[48:49], v[44:45] op_sel_hi:[0,1,1]
	v_cvt_scalef32_pk_f32_fp4 v[48:49], v177, 1.0 op_sel:[1,1,0]
	v_pk_fma_f32 v[46:47], s[26:27], v[48:49], v[46:47] op_sel_hi:[0,1,1]
	v_cvt_scalef32_pk_f32_fp4 v[48:49], v174, 1.0
	v_pk_fma_f32 v[32:33], s[28:29], v[48:49], v[32:33] op_sel_hi:[0,1,1]
	v_cvt_scalef32_pk_f32_fp4 v[48:49], v174, 1.0 op_sel:[1,0,0]
	v_pk_fma_f32 v[34:35], s[28:29], v[48:49], v[34:35] op_sel_hi:[0,1,1]
	v_cvt_scalef32_pk_f32_fp4 v[48:49], v174, 1.0 op_sel:[0,1,0]
	v_pk_fma_f32 v[36:37], s[28:29], v[48:49], v[36:37] op_sel_hi:[0,1,1]
	v_cvt_scalef32_pk_f32_fp4 v[48:49], v174, 1.0 op_sel:[1,1,0]
	v_pk_fma_f32 v[38:39], s[28:29], v[48:49], v[38:39] op_sel_hi:[0,1,1]
	v_cvt_scalef32_pk_f32_fp4 v[48:49], v175, 1.0
	v_pk_fma_f32 v[40:41], s[28:29], v[48:49], v[40:41] op_sel_hi:[0,1,1]
	v_cvt_scalef32_pk_f32_fp4 v[48:49], v175, 1.0 op_sel:[1,0,0]
	v_pk_fma_f32 v[42:43], s[28:29], v[48:49], v[42:43] op_sel_hi:[0,1,1]
	v_cvt_scalef32_pk_f32_fp4 v[48:49], v175, 1.0 op_sel:[0,1,0]
	v_pk_fma_f32 v[44:45], s[28:29], v[48:49], v[44:45] op_sel_hi:[0,1,1]
	v_cvt_scalef32_pk_f32_fp4 v[48:49], v175, 1.0 op_sel:[1,1,0]
	v_pk_fma_f32 v[46:47], s[28:29], v[48:49], v[46:47] op_sel_hi:[0,1,1]
	v_cvt_scalef32_pk_f32_fp4 v[48:49], v172, 1.0
	v_pk_fma_f32 v[200:201], s[30:31], v[48:49], v[32:33] op_sel_hi:[0,1,1]
	v_cvt_scalef32_pk_f32_fp4 v[32:33], v172, 1.0 op_sel:[1,0,0]
	v_pk_fma_f32 v[218:219], s[30:31], v[32:33], v[34:35] op_sel_hi:[0,1,1]
	v_cvt_scalef32_pk_f32_fp4 v[32:33], v172, 1.0 op_sel:[0,1,0]
	v_pk_fma_f32 v[216:217], s[30:31], v[32:33], v[36:37] op_sel_hi:[0,1,1]
	v_cvt_scalef32_pk_f32_fp4 v[32:33], v172, 1.0 op_sel:[1,1,0]
	v_pk_fma_f32 v[214:215], s[30:31], v[32:33], v[38:39] op_sel_hi:[0,1,1]
	v_cvt_scalef32_pk_f32_fp4 v[32:33], v173, 1.0
	v_pk_fma_f32 v[212:213], s[30:31], v[32:33], v[40:41] op_sel_hi:[0,1,1]
	v_cvt_scalef32_pk_f32_fp4 v[32:33], v173, 1.0 op_sel:[1,0,0]
	v_pk_fma_f32 v[210:211], s[30:31], v[32:33], v[42:43] op_sel_hi:[0,1,1]
	v_cvt_scalef32_pk_f32_fp4 v[32:33], v173, 1.0 op_sel:[0,1,0]
	v_pk_fma_f32 v[208:209], s[30:31], v[32:33], v[44:45] op_sel_hi:[0,1,1]
	v_cvt_scalef32_pk_f32_fp4 v[32:33], v173, 1.0 op_sel:[1,1,0]
	v_pk_fma_f32 v[206:207], s[30:31], v[32:33], v[46:47] op_sel_hi:[0,1,1]
	s_and_b64 vcc, exec, s[24:25]
	s_cbranch_vccnz .LBB0_900
	s_mov_b32 s26, s58
	s_add_i32 s58, s26, 16
	s_cmpk_gt_u32 s26, 0x6f
	s_cselect_b64 s[24:25], -1, 0
	s_cmpk_lt_u32 s26, 0x70
	s_cselect_b64 vcc, -1, 0
	s_bitcmp0_b32 s58, 6
	s_cselect_b64 s[10:11], -1, 0
	v_cndmask_b32_e64 v100, v116, v102, s[10:11]
	v_cndmask_b32_e32 v100, v118, v100, vcc
	s_nop 0
	s_waitcnt vmcnt(28)
	v_accvgpr_read_b32 v205, a43
	v_accvgpr_read_b32 v203, a45
	v_accvgpr_read_b32 v95, a23
	v_accvgpr_read_b32 v91, a27
	v_accvgpr_read_b32 v204, a42
	v_accvgpr_read_b32 v202, a44
	v_accvgpr_read_b32 v94, a22
	v_accvgpr_read_b32 v93, a21
	v_accvgpr_read_b32 v92, a20
	v_accvgpr_read_b32 v90, a26
	v_accvgpr_read_b32 v89, a25
	v_accvgpr_read_b32 v88, a24
	s_add_i32 s30, s26, 16
	v_readlane_b32 s28, v100, s30
	s_nop 1
	v_mad_i64_i32 v[136:137], s[10:11], s28, v130, v[96:97]
	global_load_dwordx4 a[20:23], v[136:137], off
	v_mad_i64_i32 v[136:137], s[10:11], s28, v130, v[98:99]
	global_load_dwordx2 a[42:43], v[136:137], off
	s_add_i32 s30, s26, 17
	v_readlane_b32 s28, v100, s30
	s_nop 1
	v_mad_i64_i32 v[136:137], s[10:11], s28, v130, v[96:97]
	global_load_dwordx4 a[24:27], v[136:137], off
	v_mad_i64_i32 v[136:137], s[10:11], s28, v130, v[98:99]
	global_load_dwordx2 a[44:45], v[136:137], off
	s_waitcnt vmcnt(28)
	v_accvgpr_read_b32 v199, a47
	v_accvgpr_read_b32 v197, a49
	v_accvgpr_read_b32 v87, a31
	v_mov_b64_e32 v[80:81], v[232:233]
	v_accvgpr_read_b32 v198, a46
	v_accvgpr_read_b32 v196, a48
	v_accvgpr_read_b32 v86, a30
	v_accvgpr_read_b32 v85, a29
	v_accvgpr_read_b32 v84, a28
	v_mov_b64_e32 v[82:83], v[234:235]
	s_add_i32 s30, s26, 18
	v_readlane_b32 s28, v100, s30
	s_nop 1
	v_mad_i64_i32 v[136:137], s[10:11], s28, v130, v[96:97]
	global_load_dwordx4 a[28:31], v[136:137], off
	v_mad_i64_i32 v[136:137], s[10:11], s28, v130, v[98:99]
	global_load_dwordx2 a[46:47], v[136:137], off
	s_add_i32 s30, s26, 19
	v_readlane_b32 s28, v100, s30
	s_nop 1
	v_mad_i64_i32 v[136:137], s[10:11], s28, v130, v[96:97]
	global_load_dwordx4 v[232:235], v[136:137], off
	v_mad_i64_i32 v[136:137], s[10:11], s28, v130, v[98:99]
	global_load_dwordx2 a[48:49], v[136:137], off
	s_waitcnt vmcnt(28)
	v_accvgpr_read_b32 v195, a51
	v_accvgpr_read_b32 v193, a53
	v_mov_b64_e32 v[76:77], v[236:237]
	v_mov_b64_e32 v[72:73], v[240:241]
	v_accvgpr_read_b32 v194, a50
	v_accvgpr_read_b32 v192, a52
	v_mov_b64_e32 v[78:79], v[238:239]
	v_mov_b64_e32 v[74:75], v[242:243]
	s_add_i32 s30, s26, 20
	v_readlane_b32 s28, v100, s30
	s_nop 1
	v_mad_i64_i32 v[136:137], s[10:11], s28, v130, v[96:97]
	global_load_dwordx4 v[236:239], v[136:137], off
	v_mad_i64_i32 v[136:137], s[10:11], s28, v130, v[98:99]
	global_load_dwordx2 a[50:51], v[136:137], off
	s_add_i32 s30, s26, 21
	v_readlane_b32 s28, v100, s30
	s_nop 1
	v_mad_i64_i32 v[136:137], s[10:11], s28, v130, v[96:97]
	global_load_dwordx4 v[240:243], v[136:137], off
	v_mad_i64_i32 v[136:137], s[10:11], s28, v130, v[98:99]
	global_load_dwordx2 a[52:53], v[136:137], off
	s_waitcnt vmcnt(28)
	v_accvgpr_read_b32 v191, a55
	v_accvgpr_read_b32 v189, a57
	v_mov_b64_e32 v[68:69], v[244:245]
	v_mov_b64_e32 v[64:65], v[248:249]
	v_accvgpr_read_b32 v190, a54
	v_accvgpr_read_b32 v188, a56
	v_mov_b64_e32 v[70:71], v[246:247]
	v_mov_b64_e32 v[66:67], v[250:251]
	s_add_i32 s30, s26, 22
	v_readlane_b32 s28, v100, s30
	s_nop 1
	v_mad_i64_i32 v[136:137], s[10:11], s28, v130, v[96:97]
	global_load_dwordx4 v[244:247], v[136:137], off
	v_mad_i64_i32 v[136:137], s[10:11], s28, v130, v[98:99]
	global_load_dwordx2 a[54:55], v[136:137], off
	s_add_i32 s30, s26, 23
	v_readlane_b32 s28, v100, s30
	s_nop 1
	v_mad_i64_i32 v[136:137], s[10:11], s28, v130, v[96:97]
	global_load_dwordx4 v[248:251], v[136:137], off
	v_mad_i64_i32 v[136:137], s[10:11], s28, v130, v[98:99]
	global_load_dwordx2 a[56:57], v[136:137], off
	s_waitcnt vmcnt(28)
	v_accvgpr_read_b32 v187, a59
	v_accvgpr_read_b32 v185, a61
	v_accvgpr_read_b32 v63, a3
	v_accvgpr_read_b32 v59, a7
	v_accvgpr_read_b32 v186, a58
	v_accvgpr_read_b32 v184, a60
	v_accvgpr_read_b32 v62, a2
	v_accvgpr_read_b32 v61, a1
	v_accvgpr_read_b32 v60, a0
	v_accvgpr_read_b32 v58, a6
	v_accvgpr_read_b32 v57, a5
	v_accvgpr_read_b32 v56, a4
	s_add_i32 s30, s26, 24
	v_readlane_b32 s28, v100, s30
	s_nop 1
	v_mad_i64_i32 v[136:137], s[10:11], s28, v130, v[96:97]
	global_load_dwordx4 a[0:3], v[136:137], off
	v_mad_i64_i32 v[136:137], s[10:11], s28, v130, v[98:99]
	global_load_dwordx2 a[58:59], v[136:137], off
	s_add_i32 s30, s26, 25
	v_readlane_b32 s28, v100, s30
	s_nop 1
	v_mad_i64_i32 v[136:137], s[10:11], s28, v130, v[96:97]
	global_load_dwordx4 a[4:7], v[136:137], off
	v_mad_i64_i32 v[136:137], s[10:11], s28, v130, v[98:99]
	global_load_dwordx2 a[60:61], v[136:137], off
	s_waitcnt vmcnt(28)
	v_accvgpr_read_b32 v183, a63
	v_accvgpr_read_b32 v181, a65
	v_accvgpr_read_b32 v55, a11
	v_accvgpr_read_b32 v51, a15
	v_accvgpr_read_b32 v182, a62
	v_accvgpr_read_b32 v180, a64
	v_accvgpr_read_b32 v54, a10
	v_accvgpr_read_b32 v53, a9
	v_accvgpr_read_b32 v52, a8
	v_accvgpr_read_b32 v50, a14
	v_accvgpr_read_b32 v49, a13
	v_accvgpr_read_b32 v48, a12
	s_add_i32 s30, s26, 26
	v_readlane_b32 s28, v100, s30
	s_nop 1
	v_mad_i64_i32 v[136:137], s[10:11], s28, v130, v[96:97]
	global_load_dwordx4 a[8:11], v[136:137], off
	v_mad_i64_i32 v[136:137], s[10:11], s28, v130, v[98:99]
	global_load_dwordx2 a[62:63], v[136:137], off
	s_add_i32 s30, s26, 27
	v_readlane_b32 s28, v100, s30
	s_nop 1
	v_mad_i64_i32 v[136:137], s[10:11], s28, v130, v[96:97]
	global_load_dwordx4 a[12:15], v[136:137], off
	v_mad_i64_i32 v[136:137], s[10:11], s28, v130, v[98:99]
	global_load_dwordx2 a[64:65], v[136:137], off
	s_waitcnt vmcnt(28)
	v_accvgpr_read_b32 v179, a67
	v_accvgpr_read_b32 v47, a19
	v_mov_b64_e32 v[40:41], v[220:221]
	v_accvgpr_read_b32 v178, a66
	v_mov_b64_e32 v[176:177], v[148:149]
	v_accvgpr_read_b32 v46, a18
	v_accvgpr_read_b32 v45, a17
	v_accvgpr_read_b32 v44, a16
	v_mov_b64_e32 v[42:43], v[222:223]
	s_add_i32 s30, s26, 28
	v_readlane_b32 s28, v100, s30
	s_nop 1
	v_mad_i64_i32 v[136:137], s[10:11], s28, v130, v[96:97]
	global_load_dwordx4 a[16:19], v[136:137], off
	v_mad_i64_i32 v[136:137], s[10:11], s28, v130, v[98:99]
	global_load_dwordx2 a[66:67], v[136:137], off
	s_add_i32 s30, s26, 29
	v_readlane_b32 s28, v100, s30
	s_nop 1
	v_mad_i64_i32 v[136:137], s[10:11], s28, v130, v[96:97]
	global_load_dwordx4 v[220:223], v[136:137], off
	v_mad_i64_i32 v[136:137], s[10:11], s28, v130, v[98:99]
	global_load_dwordx2 v[148:149], v[136:137], off
	s_waitcnt vmcnt(28)
	v_accvgpr_read_b32 v173, a41
	v_mov_b64_e32 v[36:37], v[224:225]
	v_mov_b64_e32 v[32:33], v[228:229]
	v_mov_b64_e32 v[174:175], v[252:253]
	v_accvgpr_read_b32 v172, a40
	v_mov_b64_e32 v[38:39], v[226:227]
	v_mov_b64_e32 v[34:35], v[230:231]
	s_add_i32 s30, s26, 30
	v_readlane_b32 s28, v100, s30
	s_nop 1
	v_mad_i64_i32 v[136:137], s[10:11], s28, v130, v[96:97]
	global_load_dwordx4 v[224:227], v[136:137], off
	v_mad_i64_i32 v[136:137], s[10:11], s28, v130, v[98:99]
	global_load_dwordx2 v[252:253], v[136:137], off
	s_add_i32 s30, s26, 31
	v_readlane_b32 s28, v100, s30
	s_nop 1
	v_mad_i64_i32 v[136:137], s[10:11], s28, v130, v[96:97]
	global_load_dwordx4 v[228:231], v[136:137], off
	v_mad_i64_i32 v[136:137], s[10:11], s28, v130, v[98:99]
	global_load_dwordx2 a[40:41], v[136:137], off
	s_cmp_lg_u32 s26, 64
	s_cbranch_scc1 .LBB0_904
	global_load_dword a68, v[170:171], off
	global_load_dword a69, v[168:169], off
	global_load_dword v117, v[166:167], off
	global_load_dword v103, v[164:165], off
	s_branch .LBB0_904

.LBB0_1403:
	s_andn2_saveexec_b64 s[50:51], s[50:51]
	v_mul_f32_e32 v34, v33, v33
	v_fmamk_f32 v35, v34, 0xba1345e1, v139
	v_fmaak_f32 v35, v34, v35, 0xbcdac9b8
	v_fmaak_f32 v35, v34, v35, 0x3de703be
	v_fmaak_f32 v35, v34, v35, 0xbec09330
	v_fmaak_f32 v34, v34, v35, 0x3e0375d0
	v_fma_f32 v34, |v33|, v34, |v33|
	s_or_b64 exec, exec, s[50:51]
	v_cvt_scalef32_pk_f32_fp4 v[36:37], v204, 1.0
	v_pk_fma_f32 v[36:37], s[30:31], v[36:37], v[200:201] op_sel_hi:[0,1,1]
	v_cvt_scalef32_pk_f32_fp4 v[38:39], v204, 1.0 op_sel:[1,0,0]
	v_cvt_scalef32_pk_f32_fp4 v[52:53], v202, 1.0
	v_pk_fma_f32 v[38:39], s[30:31], v[38:39], v[218:219] op_sel_hi:[0,1,1]
	v_cvt_scalef32_pk_f32_fp4 v[40:41], v204, 1.0 op_sel:[0,1,0]
	v_pk_fma_f32 v[36:37], s[28:29], v[52:53], v[36:37] op_sel_hi:[0,1,1]
	v_cvt_scalef32_pk_f32_fp4 v[52:53], v202, 1.0 op_sel:[1,0,0]
	v_pk_fma_f32 v[40:41], s[30:31], v[40:41], v[216:217] op_sel_hi:[0,1,1]
	v_cvt_scalef32_pk_f32_fp4 v[42:43], v204, 1.0 op_sel:[1,1,0]
	v_pk_fma_f32 v[38:39], s[28:29], v[52:53], v[38:39] op_sel_hi:[0,1,1]
	v_cvt_scalef32_pk_f32_fp4 v[52:53], v202, 1.0 op_sel:[0,1,0]
	v_pk_fma_f32 v[42:43], s[30:31], v[42:43], v[214:215] op_sel_hi:[0,1,1]
	v_cvt_scalef32_pk_f32_fp4 v[44:45], v205, 1.0
	v_pk_fma_f32 v[40:41], s[28:29], v[52:53], v[40:41] op_sel_hi:[0,1,1]
	v_cvt_scalef32_pk_f32_fp4 v[52:53], v202, 1.0 op_sel:[1,1,0]
	v_pk_fma_f32 v[44:45], s[30:31], v[44:45], v[212:213] op_sel_hi:[0,1,1]
	v_cvt_scalef32_pk_f32_fp4 v[46:47], v205, 1.0 op_sel:[1,0,0]
	v_pk_fma_f32 v[42:43], s[28:29], v[52:53], v[42:43] op_sel_hi:[0,1,1]
	v_cvt_scalef32_pk_f32_fp4 v[52:53], v203, 1.0
	v_pk_fma_f32 v[46:47], s[30:31], v[46:47], v[210:211] op_sel_hi:[0,1,1]
	v_cvt_scalef32_pk_f32_fp4 v[48:49], v205, 1.0 op_sel:[0,1,0]
	v_pk_fma_f32 v[44:45], s[28:29], v[52:53], v[44:45] op_sel_hi:[0,1,1]
	v_cvt_scalef32_pk_f32_fp4 v[52:53], v203, 1.0 op_sel:[1,0,0]
	v_pk_fma_f32 v[48:49], s[30:31], v[48:49], v[208:209] op_sel_hi:[0,1,1]
	v_cvt_scalef32_pk_f32_fp4 v[50:51], v205, 1.0 op_sel:[1,1,0]
	v_pk_fma_f32 v[46:47], s[28:29], v[52:53], v[46:47] op_sel_hi:[0,1,1]
	v_cvt_scalef32_pk_f32_fp4 v[52:53], v203, 1.0 op_sel:[0,1,0]
	v_pk_fma_f32 v[50:51], s[30:31], v[50:51], v[206:207] op_sel_hi:[0,1,1]
	v_pk_fma_f32 v[48:49], s[28:29], v[52:53], v[48:49] op_sel_hi:[0,1,1]
	v_cvt_scalef32_pk_f32_fp4 v[52:53], v203, 1.0 op_sel:[1,1,0]
	v_pk_fma_f32 v[50:51], s[28:29], v[52:53], v[50:51] op_sel_hi:[0,1,1]
	v_cvt_scalef32_pk_f32_fp4 v[52:53], v198, 1.0
	v_pk_fma_f32 v[36:37], s[26:27], v[52:53], v[36:37] op_sel_hi:[0,1,1]
	v_cvt_scalef32_pk_f32_fp4 v[52:53], v198, 1.0 op_sel:[1,0,0]
	v_pk_fma_f32 v[38:39], s[26:27], v[52:53], v[38:39] op_sel_hi:[0,1,1]
	v_cvt_scalef32_pk_f32_fp4 v[52:53], v198, 1.0 op_sel:[0,1,0]
	v_pk_fma_f32 v[40:41], s[26:27], v[52:53], v[40:41] op_sel_hi:[0,1,1]
	v_cvt_scalef32_pk_f32_fp4 v[52:53], v198, 1.0 op_sel:[1,1,0]
	v_pk_fma_f32 v[42:43], s[26:27], v[52:53], v[42:43] op_sel_hi:[0,1,1]
	v_cvt_scalef32_pk_f32_fp4 v[52:53], v199, 1.0
	v_pk_fma_f32 v[44:45], s[26:27], v[52:53], v[44:45] op_sel_hi:[0,1,1]
	v_cvt_scalef32_pk_f32_fp4 v[52:53], v199, 1.0 op_sel:[1,0,0]
	v_pk_fma_f32 v[46:47], s[26:27], v[52:53], v[46:47] op_sel_hi:[0,1,1]
	v_cvt_scalef32_pk_f32_fp4 v[52:53], v199, 1.0 op_sel:[0,1,0]
	v_pk_fma_f32 v[48:49], s[26:27], v[52:53], v[48:49] op_sel_hi:[0,1,1]
	v_cvt_scalef32_pk_f32_fp4 v[52:53], v199, 1.0 op_sel:[1,1,0]
	v_pk_fma_f32 v[50:51], s[26:27], v[52:53], v[50:51] op_sel_hi:[0,1,1]
	v_cvt_scalef32_pk_f32_fp4 v[52:53], v196, 1.0
	v_pk_fma_f32 v[36:37], s[12:13], v[52:53], v[36:37] op_sel_hi:[0,1,1]
	v_cvt_scalef32_pk_f32_fp4 v[52:53], v196, 1.0 op_sel:[1,0,0]
	v_pk_fma_f32 v[38:39], s[12:13], v[52:53], v[38:39] op_sel_hi:[0,1,1]
	v_cvt_scalef32_pk_f32_fp4 v[52:53], v196, 1.0 op_sel:[0,1,0]
	v_pk_fma_f32 v[40:41], s[12:13], v[52:53], v[40:41] op_sel_hi:[0,1,1]
	v_cvt_scalef32_pk_f32_fp4 v[52:53], v196, 1.0 op_sel:[1,1,0]
	v_pk_fma_f32 v[42:43], s[12:13], v[52:53], v[42:43] op_sel_hi:[0,1,1]
	v_cvt_scalef32_pk_f32_fp4 v[52:53], v197, 1.0
	v_pk_fma_f32 v[44:45], s[12:13], v[52:53], v[44:45] op_sel_hi:[0,1,1]
	v_cvt_scalef32_pk_f32_fp4 v[52:53], v197, 1.0 op_sel:[1,0,0]
	v_pk_fma_f32 v[46:47], s[12:13], v[52:53], v[46:47] op_sel_hi:[0,1,1]
	v_cvt_scalef32_pk_f32_fp4 v[52:53], v197, 1.0 op_sel:[0,1,0]
	v_pk_fma_f32 v[48:49], s[12:13], v[52:53], v[48:49] op_sel_hi:[0,1,1]
	v_cvt_scalef32_pk_f32_fp4 v[52:53], v197, 1.0 op_sel:[1,1,0]
	v_pk_fma_f32 v[50:51], s[12:13], v[52:53], v[50:51] op_sel_hi:[0,1,1]
	v_cvt_scalef32_pk_f32_fp4 v[52:53], v194, 1.0
	v_pk_fma_f32 v[36:37], s[40:41], v[52:53], v[36:37] op_sel_hi:[0,1,1]
	v_cvt_scalef32_pk_f32_fp4 v[52:53], v194, 1.0 op_sel:[1,0,0]
	v_pk_fma_f32 v[38:39], s[40:41], v[52:53], v[38:39] op_sel_hi:[0,1,1]
	v_cvt_scalef32_pk_f32_fp4 v[52:53], v194, 1.0 op_sel:[0,1,0]
	v_pk_fma_f32 v[40:41], s[40:41], v[52:53], v[40:41] op_sel_hi:[0,1,1]
	v_cvt_scalef32_pk_f32_fp4 v[52:53], v194, 1.0 op_sel:[1,1,0]
	v_pk_fma_f32 v[42:43], s[40:41], v[52:53], v[42:43] op_sel_hi:[0,1,1]
	v_cvt_scalef32_pk_f32_fp4 v[52:53], v195, 1.0
	v_pk_fma_f32 v[44:45], s[40:41], v[52:53], v[44:45] op_sel_hi:[0,1,1]
	v_cvt_scalef32_pk_f32_fp4 v[52:53], v195, 1.0 op_sel:[1,0,0]
	v_pk_fma_f32 v[46:47], s[40:41], v[52:53], v[46:47] op_sel_hi:[0,1,1]
	v_cvt_scalef32_pk_f32_fp4 v[52:53], v195, 1.0 op_sel:[0,1,0]
	v_pk_fma_f32 v[48:49], s[40:41], v[52:53], v[48:49] op_sel_hi:[0,1,1]
	v_cvt_scalef32_pk_f32_fp4 v[52:53], v195, 1.0 op_sel:[1,1,0]
	v_pk_fma_f32 v[50:51], s[40:41], v[52:53], v[50:51] op_sel_hi:[0,1,1]
	v_cvt_scalef32_pk_f32_fp4 v[52:53], v192, 1.0
	v_pk_fma_f32 v[36:37], s[38:39], v[52:53], v[36:37] op_sel_hi:[0,1,1]
	v_cvt_scalef32_pk_f32_fp4 v[52:53], v192, 1.0 op_sel:[1,0,0]
	v_pk_fma_f32 v[38:39], s[38:39], v[52:53], v[38:39] op_sel_hi:[0,1,1]
	v_cvt_scalef32_pk_f32_fp4 v[52:53], v192, 1.0 op_sel:[0,1,0]
	v_pk_fma_f32 v[40:41], s[38:39], v[52:53], v[40:41] op_sel_hi:[0,1,1]
	v_cvt_scalef32_pk_f32_fp4 v[52:53], v192, 1.0 op_sel:[1,1,0]
	v_pk_fma_f32 v[42:43], s[38:39], v[52:53], v[42:43] op_sel_hi:[0,1,1]
	v_cvt_scalef32_pk_f32_fp4 v[52:53], v193, 1.0
	v_pk_fma_f32 v[44:45], s[38:39], v[52:53], v[44:45] op_sel_hi:[0,1,1]
	v_cvt_scalef32_pk_f32_fp4 v[52:53], v193, 1.0 op_sel:[1,0,0]
	v_pk_fma_f32 v[46:47], s[38:39], v[52:53], v[46:47] op_sel_hi:[0,1,1]
	v_cvt_scalef32_pk_f32_fp4 v[52:53], v193, 1.0 op_sel:[0,1,0]
	v_pk_fma_f32 v[48:49], s[38:39], v[52:53], v[48:49] op_sel_hi:[0,1,1]
	v_cvt_scalef32_pk_f32_fp4 v[52:53], v193, 1.0 op_sel:[1,1,0]
	v_pk_fma_f32 v[50:51], s[38:39], v[52:53], v[50:51] op_sel_hi:[0,1,1]
	v_cvt_scalef32_pk_f32_fp4 v[52:53], v190, 1.0
	v_pk_fma_f32 v[36:37], s[36:37], v[52:53], v[36:37] op_sel_hi:[0,1,1]
	v_cvt_scalef32_pk_f32_fp4 v[52:53], v190, 1.0 op_sel:[1,0,0]
	v_pk_fma_f32 v[38:39], s[36:37], v[52:53], v[38:39] op_sel_hi:[0,1,1]
	v_cvt_scalef32_pk_f32_fp4 v[52:53], v190, 1.0 op_sel:[0,1,0]
	v_pk_fma_f32 v[40:41], s[36:37], v[52:53], v[40:41] op_sel_hi:[0,1,1]
	v_cvt_scalef32_pk_f32_fp4 v[52:53], v190, 1.0 op_sel:[1,1,0]
	v_pk_fma_f32 v[42:43], s[36:37], v[52:53], v[42:43] op_sel_hi:[0,1,1]
	v_cvt_scalef32_pk_f32_fp4 v[52:53], v191, 1.0
	v_pk_fma_f32 v[44:45], s[36:37], v[52:53], v[44:45] op_sel_hi:[0,1,1]
	v_cvt_scalef32_pk_f32_fp4 v[52:53], v191, 1.0 op_sel:[1,0,0]
	v_pk_fma_f32 v[46:47], s[36:37], v[52:53], v[46:47] op_sel_hi:[0,1,1]
	v_cvt_scalef32_pk_f32_fp4 v[52:53], v191, 1.0 op_sel:[0,1,0]
	v_pk_fma_f32 v[48:49], s[36:37], v[52:53], v[48:49] op_sel_hi:[0,1,1]
	v_cvt_scalef32_pk_f32_fp4 v[52:53], v191, 1.0 op_sel:[1,1,0]
	v_pk_fma_f32 v[50:51], s[36:37], v[52:53], v[50:51] op_sel_hi:[0,1,1]
	v_cvt_scalef32_pk_f32_fp4 v[52:53], v188, 1.0
	v_pk_fma_f32 v[36:37], s[34:35], v[52:53], v[36:37] op_sel_hi:[0,1,1]
	v_cvt_scalef32_pk_f32_fp4 v[52:53], v188, 1.0 op_sel:[1,0,0]
	v_pk_fma_f32 v[38:39], s[34:35], v[52:53], v[38:39] op_sel_hi:[0,1,1]
	v_cvt_scalef32_pk_f32_fp4 v[52:53], v188, 1.0 op_sel:[0,1,0]
	v_pk_fma_f32 v[40:41], s[34:35], v[52:53], v[40:41] op_sel_hi:[0,1,1]
	v_cvt_scalef32_pk_f32_fp4 v[52:53], v188, 1.0 op_sel:[1,1,0]
	v_pk_fma_f32 v[42:43], s[34:35], v[52:53], v[42:43] op_sel_hi:[0,1,1]
	v_cvt_scalef32_pk_f32_fp4 v[52:53], v189, 1.0
	v_pk_fma_f32 v[44:45], s[34:35], v[52:53], v[44:45] op_sel_hi:[0,1,1]
	v_cvt_scalef32_pk_f32_fp4 v[52:53], v189, 1.0 op_sel:[1,0,0]
	v_pk_fma_f32 v[46:47], s[34:35], v[52:53], v[46:47] op_sel_hi:[0,1,1]
	v_cvt_scalef32_pk_f32_fp4 v[52:53], v189, 1.0 op_sel:[0,1,0]
	v_pk_fma_f32 v[48:49], s[34:35], v[52:53], v[48:49] op_sel_hi:[0,1,1]
	v_cvt_scalef32_pk_f32_fp4 v[52:53], v189, 1.0 op_sel:[1,1,0]
	v_pk_fma_f32 v[50:51], s[34:35], v[52:53], v[50:51] op_sel_hi:[0,1,1]
	v_cvt_scalef32_pk_f32_fp4 v[52:53], v186, 1.0
	v_pk_fma_f32 v[36:37], s[48:49], v[52:53], v[36:37] op_sel_hi:[0,1,1]
	v_cvt_scalef32_pk_f32_fp4 v[52:53], v186, 1.0 op_sel:[1,0,0]
	v_pk_fma_f32 v[38:39], s[48:49], v[52:53], v[38:39] op_sel_hi:[0,1,1]
	v_cvt_scalef32_pk_f32_fp4 v[52:53], v186, 1.0 op_sel:[0,1,0]
	v_pk_fma_f32 v[40:41], s[48:49], v[52:53], v[40:41] op_sel_hi:[0,1,1]
	v_cvt_scalef32_pk_f32_fp4 v[52:53], v186, 1.0 op_sel:[1,1,0]
	v_pk_fma_f32 v[42:43], s[48:49], v[52:53], v[42:43] op_sel_hi:[0,1,1]
	v_cvt_scalef32_pk_f32_fp4 v[52:53], v187, 1.0
	v_pk_fma_f32 v[44:45], s[48:49], v[52:53], v[44:45] op_sel_hi:[0,1,1]
	v_cvt_scalef32_pk_f32_fp4 v[52:53], v187, 1.0 op_sel:[1,0,0]
	v_pk_fma_f32 v[46:47], s[48:49], v[52:53], v[46:47] op_sel_hi:[0,1,1]
	v_cvt_scalef32_pk_f32_fp4 v[52:53], v187, 1.0 op_sel:[0,1,0]
	v_pk_fma_f32 v[48:49], s[48:49], v[52:53], v[48:49] op_sel_hi:[0,1,1]
	v_cvt_scalef32_pk_f32_fp4 v[52:53], v187, 1.0 op_sel:[1,1,0]
	v_pk_fma_f32 v[50:51], s[48:49], v[52:53], v[50:51] op_sel_hi:[0,1,1]
	v_cvt_scalef32_pk_f32_fp4 v[52:53], v184, 1.0
	v_pk_fma_f32 v[36:37], s[46:47], v[52:53], v[36:37] op_sel_hi:[0,1,1]
	v_cvt_scalef32_pk_f32_fp4 v[52:53], v184, 1.0 op_sel:[1,0,0]
	v_pk_fma_f32 v[38:39], s[46:47], v[52:53], v[38:39] op_sel_hi:[0,1,1]
	v_cvt_scalef32_pk_f32_fp4 v[52:53], v184, 1.0 op_sel:[0,1,0]
	v_pk_fma_f32 v[40:41], s[46:47], v[52:53], v[40:41] op_sel_hi:[0,1,1]
	v_cvt_scalef32_pk_f32_fp4 v[52:53], v184, 1.0 op_sel:[1,1,0]
	v_pk_fma_f32 v[42:43], s[46:47], v[52:53], v[42:43] op_sel_hi:[0,1,1]
	v_cvt_scalef32_pk_f32_fp4 v[52:53], v185, 1.0
	v_pk_fma_f32 v[44:45], s[46:47], v[52:53], v[44:45] op_sel_hi:[0,1,1]
	v_cvt_scalef32_pk_f32_fp4 v[52:53], v185, 1.0 op_sel:[1,0,0]
	v_pk_fma_f32 v[46:47], s[46:47], v[52:53], v[46:47] op_sel_hi:[0,1,1]
	v_cvt_scalef32_pk_f32_fp4 v[52:53], v185, 1.0 op_sel:[0,1,0]
	v_pk_fma_f32 v[48:49], s[46:47], v[52:53], v[48:49] op_sel_hi:[0,1,1]
	v_cvt_scalef32_pk_f32_fp4 v[52:53], v185, 1.0 op_sel:[1,1,0]
	v_pk_fma_f32 v[50:51], s[46:47], v[52:53], v[50:51] op_sel_hi:[0,1,1]
	v_cvt_scalef32_pk_f32_fp4 v[52:53], v182, 1.0
	v_pk_fma_f32 v[36:37], s[44:45], v[52:53], v[36:37] op_sel_hi:[0,1,1]
	v_cvt_scalef32_pk_f32_fp4 v[52:53], v182, 1.0 op_sel:[1,0,0]
	v_pk_fma_f32 v[38:39], s[44:45], v[52:53], v[38:39] op_sel_hi:[0,1,1]
	v_cvt_scalef32_pk_f32_fp4 v[52:53], v182, 1.0 op_sel:[0,1,0]
	v_pk_fma_f32 v[40:41], s[44:45], v[52:53], v[40:41] op_sel_hi:[0,1,1]
	v_cvt_scalef32_pk_f32_fp4 v[52:53], v182, 1.0 op_sel:[1,1,0]
	v_pk_fma_f32 v[42:43], s[44:45], v[52:53], v[42:43] op_sel_hi:[0,1,1]
	v_cvt_scalef32_pk_f32_fp4 v[52:53], v183, 1.0
	v_pk_fma_f32 v[44:45], s[44:45], v[52:53], v[44:45] op_sel_hi:[0,1,1]
	v_cvt_scalef32_pk_f32_fp4 v[52:53], v183, 1.0 op_sel:[1,0,0]
	v_pk_fma_f32 v[46:47], s[44:45], v[52:53], v[46:47] op_sel_hi:[0,1,1]
	v_cvt_scalef32_pk_f32_fp4 v[52:53], v183, 1.0 op_sel:[0,1,0]
	v_pk_fma_f32 v[48:49], s[44:45], v[52:53], v[48:49] op_sel_hi:[0,1,1]
	v_cvt_scalef32_pk_f32_fp4 v[52:53], v183, 1.0 op_sel:[1,1,0]
	v_pk_fma_f32 v[50:51], s[44:45], v[52:53], v[50:51] op_sel_hi:[0,1,1]
	v_cvt_scalef32_pk_f32_fp4 v[52:53], v180, 1.0
	v_pk_fma_f32 v[36:37], s[42:43], v[52:53], v[36:37] op_sel_hi:[0,1,1]
	v_cvt_scalef32_pk_f32_fp4 v[52:53], v180, 1.0 op_sel:[1,0,0]
	v_pk_fma_f32 v[38:39], s[42:43], v[52:53], v[38:39] op_sel_hi:[0,1,1]
	v_cvt_scalef32_pk_f32_fp4 v[52:53], v180, 1.0 op_sel:[0,1,0]
	v_pk_fma_f32 v[40:41], s[42:43], v[52:53], v[40:41] op_sel_hi:[0,1,1]
	v_cvt_scalef32_pk_f32_fp4 v[52:53], v180, 1.0 op_sel:[1,1,0]
	v_pk_fma_f32 v[42:43], s[42:43], v[52:53], v[42:43] op_sel_hi:[0,1,1]
	v_cvt_scalef32_pk_f32_fp4 v[52:53], v181, 1.0
	v_pk_fma_f32 v[44:45], s[42:43], v[52:53], v[44:45] op_sel_hi:[0,1,1]
	v_cvt_scalef32_pk_f32_fp4 v[52:53], v181, 1.0 op_sel:[1,0,0]
	v_pk_fma_f32 v[46:47], s[42:43], v[52:53], v[46:47] op_sel_hi:[0,1,1]
	v_cvt_scalef32_pk_f32_fp4 v[52:53], v181, 1.0 op_sel:[0,1,0]
	v_pk_fma_f32 v[48:49], s[42:43], v[52:53], v[48:49] op_sel_hi:[0,1,1]
	v_cvt_scalef32_pk_f32_fp4 v[52:53], v181, 1.0 op_sel:[1,1,0]
	v_pk_fma_f32 v[50:51], s[42:43], v[52:53], v[50:51] op_sel_hi:[0,1,1]
	v_mov_b32_e32 v35, s59
	v_mov_b32_e32 v52, s35
	v_cndmask_b32_e64 v35, v35, v52, s[10:11]
	v_mov_b32_e32 v52, s43
	v_bfi_b32 v33, s55, v34, v33
	v_cndmask_b32_e64 v35, v35, v52, s[8:9]
	v_mov_b32_e32 v52, s13
	v_mul_f32_e32 v32, 0.5, v32
	v_add_f32_e32 v33, 1.0, v33
	v_cndmask_b32_e64 v35, v35, v52, s[6:7]
	v_mul_f32_e32 v32, v32, v33
	v_mul_f32_e32 v32, v35, v32
	v_cvt_scalef32_pk_f32_fp4 v[34:35], v178, 1.0 op_sel:[1,0,0]
	v_readlane_b32 s12, v32, 0
	v_readlane_b32 s26, v32, 32
	v_readlane_b32 s28, v32, 16
	v_readlane_b32 s30, v32, 48
	v_cvt_scalef32_pk_f32_fp4 v[32:33], v178, 1.0
	v_pk_fma_f32 v[32:33], s[12:13], v[32:33], v[36:37] op_sel_hi:[0,1,1]
	v_cvt_scalef32_pk_f32_fp4 v[36:37], v178, 1.0 op_sel:[0,1,0]
	v_pk_fma_f32 v[36:37], s[12:13], v[36:37], v[40:41] op_sel_hi:[0,1,1]
	v_cvt_scalef32_pk_f32_fp4 v[40:41], v179, 1.0
	v_pk_fma_f32 v[40:41], s[12:13], v[40:41], v[44:45] op_sel_hi:[0,1,1]
	v_cvt_scalef32_pk_f32_fp4 v[44:45], v179, 1.0 op_sel:[0,1,0]
	v_pk_fma_f32 v[44:45], s[12:13], v[44:45], v[48:49] op_sel_hi:[0,1,1]
	v_cvt_scalef32_pk_f32_fp4 v[48:49], v176, 1.0
	v_pk_fma_f32 v[34:35], s[12:13], v[34:35], v[38:39] op_sel_hi:[0,1,1]
	v_pk_fma_f32 v[32:33], s[26:27], v[48:49], v[32:33] op_sel_hi:[0,1,1]
	v_cvt_scalef32_pk_f32_fp4 v[48:49], v176, 1.0 op_sel:[1,0,0]
	v_cvt_scalef32_pk_f32_fp4 v[38:39], v178, 1.0 op_sel:[1,1,0]
	v_pk_fma_f32 v[34:35], s[26:27], v[48:49], v[34:35] op_sel_hi:[0,1,1]
	v_cvt_scalef32_pk_f32_fp4 v[48:49], v176, 1.0 op_sel:[0,1,0]
	v_pk_fma_f32 v[38:39], s[12:13], v[38:39], v[42:43] op_sel_hi:[0,1,1]
	v_pk_fma_f32 v[36:37], s[26:27], v[48:49], v[36:37] op_sel_hi:[0,1,1]
	v_cvt_scalef32_pk_f32_fp4 v[48:49], v176, 1.0 op_sel:[1,1,0]
	v_cvt_scalef32_pk_f32_fp4 v[42:43], v179, 1.0 op_sel:[1,0,0]
	v_pk_fma_f32 v[38:39], s[26:27], v[48:49], v[38:39] op_sel_hi:[0,1,1]
	v_cvt_scalef32_pk_f32_fp4 v[48:49], v177, 1.0
	v_pk_fma_f32 v[42:43], s[12:13], v[42:43], v[46:47] op_sel_hi:[0,1,1]
	v_pk_fma_f32 v[40:41], s[26:27], v[48:49], v[40:41] op_sel_hi:[0,1,1]
	v_cvt_scalef32_pk_f32_fp4 v[48:49], v177, 1.0 op_sel:[1,0,0]
	v_cvt_scalef32_pk_f32_fp4 v[46:47], v179, 1.0 op_sel:[1,1,0]
	v_pk_fma_f32 v[42:43], s[26:27], v[48:49], v[42:43] op_sel_hi:[0,1,1]
	v_cvt_scalef32_pk_f32_fp4 v[48:49], v177, 1.0 op_sel:[0,1,0]
	v_pk_fma_f32 v[46:47], s[12:13], v[46:47], v[50:51] op_sel_hi:[0,1,1]
	v_pk_fma_f32 v[44:45], s[26:27], v[48:49], v[44:45] op_sel_hi:[0,1,1]
	v_cvt_scalef32_pk_f32_fp4 v[48:49], v177, 1.0 op_sel:[1,1,0]
	v_pk_fma_f32 v[46:47], s[26:27], v[48:49], v[46:47] op_sel_hi:[0,1,1]
	v_cvt_scalef32_pk_f32_fp4 v[48:49], v174, 1.0
	v_pk_fma_f32 v[32:33], s[28:29], v[48:49], v[32:33] op_sel_hi:[0,1,1]
	v_cvt_scalef32_pk_f32_fp4 v[48:49], v174, 1.0 op_sel:[1,0,0]
	v_pk_fma_f32 v[34:35], s[28:29], v[48:49], v[34:35] op_sel_hi:[0,1,1]
	v_cvt_scalef32_pk_f32_fp4 v[48:49], v174, 1.0 op_sel:[0,1,0]
	v_pk_fma_f32 v[36:37], s[28:29], v[48:49], v[36:37] op_sel_hi:[0,1,1]
	v_cvt_scalef32_pk_f32_fp4 v[48:49], v174, 1.0 op_sel:[1,1,0]
	v_pk_fma_f32 v[38:39], s[28:29], v[48:49], v[38:39] op_sel_hi:[0,1,1]
	v_cvt_scalef32_pk_f32_fp4 v[48:49], v175, 1.0
	v_pk_fma_f32 v[40:41], s[28:29], v[48:49], v[40:41] op_sel_hi:[0,1,1]
	v_cvt_scalef32_pk_f32_fp4 v[48:49], v175, 1.0 op_sel:[1,0,0]
	v_pk_fma_f32 v[42:43], s[28:29], v[48:49], v[42:43] op_sel_hi:[0,1,1]
	v_cvt_scalef32_pk_f32_fp4 v[48:49], v175, 1.0 op_sel:[0,1,0]
	v_pk_fma_f32 v[44:45], s[28:29], v[48:49], v[44:45] op_sel_hi:[0,1,1]
	v_cvt_scalef32_pk_f32_fp4 v[48:49], v175, 1.0 op_sel:[1,1,0]
	v_pk_fma_f32 v[46:47], s[28:29], v[48:49], v[46:47] op_sel_hi:[0,1,1]
	v_cvt_scalef32_pk_f32_fp4 v[48:49], v172, 1.0
	v_pk_fma_f32 v[200:201], s[30:31], v[48:49], v[32:33] op_sel_hi:[0,1,1]
	v_cvt_scalef32_pk_f32_fp4 v[32:33], v172, 1.0 op_sel:[1,0,0]
	v_pk_fma_f32 v[218:219], s[30:31], v[32:33], v[34:35] op_sel_hi:[0,1,1]
	v_cvt_scalef32_pk_f32_fp4 v[32:33], v172, 1.0 op_sel:[0,1,0]
	v_pk_fma_f32 v[216:217], s[30:31], v[32:33], v[36:37] op_sel_hi:[0,1,1]
	v_cvt_scalef32_pk_f32_fp4 v[32:33], v172, 1.0 op_sel:[1,1,0]
	v_pk_fma_f32 v[214:215], s[30:31], v[32:33], v[38:39] op_sel_hi:[0,1,1]
	v_cvt_scalef32_pk_f32_fp4 v[32:33], v173, 1.0
	v_pk_fma_f32 v[212:213], s[30:31], v[32:33], v[40:41] op_sel_hi:[0,1,1]
	v_cvt_scalef32_pk_f32_fp4 v[32:33], v173, 1.0 op_sel:[1,0,0]
	v_pk_fma_f32 v[210:211], s[30:31], v[32:33], v[42:43] op_sel_hi:[0,1,1]
	v_cvt_scalef32_pk_f32_fp4 v[32:33], v173, 1.0 op_sel:[0,1,0]
	v_pk_fma_f32 v[208:209], s[30:31], v[32:33], v[44:45] op_sel_hi:[0,1,1]
	v_cvt_scalef32_pk_f32_fp4 v[32:33], v173, 1.0 op_sel:[1,1,0]
	v_pk_fma_f32 v[206:207], s[30:31], v[32:33], v[46:47] op_sel_hi:[0,1,1]
	s_and_b64 vcc, exec, s[24:25]
	s_cbranch_vccnz .LBB0_1385
	s_mov_b32 s26, s58
	s_add_i32 s58, s26, 16
	s_cmpk_gt_u32 s26, 0x6f
	s_cselect_b64 s[24:25], -1, 0
	s_cmpk_lt_u32 s26, 0x70
	s_cselect_b64 vcc, -1, 0
	s_bitcmp0_b32 s58, 6
	s_cselect_b64 s[12:13], -1, 0
	v_cndmask_b32_e64 v100, v116, v104, s[12:13]
	v_cndmask_b32_e32 v100, v118, v100, vcc
	s_nop 0
	s_waitcnt vmcnt(28)
	v_accvgpr_read_b32 v205, a43
	v_accvgpr_read_b32 v203, a45
	v_accvgpr_read_b32 v95, a23
	v_accvgpr_read_b32 v91, a31
	v_accvgpr_read_b32 v204, a42
	v_accvgpr_read_b32 v202, a44
	v_accvgpr_read_b32 v94, a22
	v_accvgpr_read_b32 v93, a21
	v_accvgpr_read_b32 v92, a20
	v_accvgpr_read_b32 v90, a30
	v_accvgpr_read_b32 v89, a29
	v_accvgpr_read_b32 v88, a28
	s_add_i32 s30, s26, 16
	v_readlane_b32 s28, v100, s30
	s_nop 1
	v_mad_i64_i32 v[136:137], s[12:13], s28, v130, v[96:97]
	global_load_dwordx4 a[20:23], v[136:137], off
	v_mad_i64_i32 v[136:137], s[12:13], s28, v130, v[98:99]
	global_load_dwordx2 a[42:43], v[136:137], off
	s_add_i32 s30, s26, 17
	v_readlane_b32 s28, v100, s30
	s_nop 1
	v_mad_i64_i32 v[136:137], s[12:13], s28, v130, v[96:97]
	global_load_dwordx4 a[28:31], v[136:137], off
	v_mad_i64_i32 v[136:137], s[12:13], s28, v130, v[98:99]
	global_load_dwordx2 a[44:45], v[136:137], off
	s_waitcnt vmcnt(28)
	v_accvgpr_read_b32 v199, a47
	v_accvgpr_read_b32 v197, a49
	v_mov_b64_e32 v[84:85], v[232:233]
	v_mov_b64_e32 v[80:81], v[236:237]
	v_accvgpr_read_b32 v198, a46
	v_accvgpr_read_b32 v196, a48
	v_mov_b64_e32 v[86:87], v[234:235]
	v_mov_b64_e32 v[82:83], v[238:239]
	s_add_i32 s30, s26, 18
	v_readlane_b32 s28, v100, s30
	s_nop 1
	v_mad_i64_i32 v[136:137], s[12:13], s28, v130, v[96:97]
	global_load_dwordx4 v[232:235], v[136:137], off
	v_mad_i64_i32 v[136:137], s[12:13], s28, v130, v[98:99]
	global_load_dwordx2 a[46:47], v[136:137], off
	s_add_i32 s30, s26, 19
	v_readlane_b32 s28, v100, s30
	s_nop 1
	v_mad_i64_i32 v[136:137], s[12:13], s28, v130, v[96:97]
	global_load_dwordx4 v[236:239], v[136:137], off
	v_mad_i64_i32 v[136:137], s[12:13], s28, v130, v[98:99]
	global_load_dwordx2 a[48:49], v[136:137], off
	s_waitcnt vmcnt(28)
	v_accvgpr_read_b32 v195, a51
	v_accvgpr_read_b32 v193, a53
	v_mov_b64_e32 v[76:77], v[240:241]
	v_mov_b64_e32 v[72:73], v[244:245]
	v_accvgpr_read_b32 v194, a50
	v_accvgpr_read_b32 v192, a52
	v_mov_b64_e32 v[78:79], v[242:243]
	v_mov_b64_e32 v[74:75], v[246:247]
	s_add_i32 s30, s26, 20
	v_readlane_b32 s28, v100, s30
	s_nop 1
	v_mad_i64_i32 v[136:137], s[12:13], s28, v130, v[96:97]
	global_load_dwordx4 v[240:243], v[136:137], off
	v_mad_i64_i32 v[136:137], s[12:13], s28, v130, v[98:99]
	global_load_dwordx2 a[50:51], v[136:137], off
	s_add_i32 s30, s26, 21
	v_readlane_b32 s28, v100, s30
	s_nop 1
	v_mad_i64_i32 v[136:137], s[12:13], s28, v130, v[96:97]
	global_load_dwordx4 v[244:247], v[136:137], off
	v_mad_i64_i32 v[136:137], s[12:13], s28, v130, v[98:99]
	global_load_dwordx2 a[52:53], v[136:137], off
	s_waitcnt vmcnt(28)
	v_accvgpr_read_b32 v191, a55
	v_accvgpr_read_b32 v189, a57
	v_mov_b64_e32 v[68:69], v[248:249]
	v_accvgpr_read_b32 v67, a3
	v_accvgpr_read_b32 v190, a54
	v_accvgpr_read_b32 v188, a56
	v_mov_b64_e32 v[70:71], v[250:251]
	v_accvgpr_read_b32 v66, a2
	v_accvgpr_read_b32 v65, a1
	v_accvgpr_read_b32 v64, a0
	s_add_i32 s30, s26, 22
	v_readlane_b32 s28, v100, s30
	s_nop 1
	v_mad_i64_i32 v[136:137], s[12:13], s28, v130, v[96:97]
	global_load_dwordx4 v[248:251], v[136:137], off
	v_mad_i64_i32 v[136:137], s[12:13], s28, v130, v[98:99]
	global_load_dwordx2 a[54:55], v[136:137], off
	s_add_i32 s30, s26, 23
	v_readlane_b32 s28, v100, s30
	s_nop 1
	v_mad_i64_i32 v[136:137], s[12:13], s28, v130, v[96:97]
	global_load_dwordx4 a[0:3], v[136:137], off
	v_mad_i64_i32 v[136:137], s[12:13], s28, v130, v[98:99]
	global_load_dwordx2 a[56:57], v[136:137], off
	s_waitcnt vmcnt(28)
	v_accvgpr_read_b32 v187, a59
	v_accvgpr_read_b32 v185, a61
	v_accvgpr_read_b32 v63, a7
	v_accvgpr_read_b32 v59, a11
	v_accvgpr_read_b32 v186, a58
	v_accvgpr_read_b32 v184, a60
	v_accvgpr_read_b32 v62, a6
	v_accvgpr_read_b32 v61, a5
	v_accvgpr_read_b32 v60, a4
	v_accvgpr_read_b32 v58, a10
	v_accvgpr_read_b32 v57, a9
	v_accvgpr_read_b32 v56, a8
	s_add_i32 s30, s26, 24
	v_readlane_b32 s28, v100, s30
	s_nop 1
	v_mad_i64_i32 v[136:137], s[12:13], s28, v130, v[96:97]
	global_load_dwordx4 a[4:7], v[136:137], off
	v_mad_i64_i32 v[136:137], s[12:13], s28, v130, v[98:99]
	global_load_dwordx2 a[58:59], v[136:137], off
	s_add_i32 s30, s26, 25
	v_readlane_b32 s28, v100, s30
	s_nop 1
	v_mad_i64_i32 v[136:137], s[12:13], s28, v130, v[96:97]
	global_load_dwordx4 a[8:11], v[136:137], off
	v_mad_i64_i32 v[136:137], s[12:13], s28, v130, v[98:99]
	global_load_dwordx2 a[60:61], v[136:137], off
	s_waitcnt vmcnt(28)
	v_accvgpr_read_b32 v183, a63
	v_accvgpr_read_b32 v181, a65
	v_accvgpr_read_b32 v55, a15
	v_accvgpr_read_b32 v51, a19
	v_accvgpr_read_b32 v182, a62
	v_accvgpr_read_b32 v180, a64
	v_accvgpr_read_b32 v54, a14
	v_accvgpr_read_b32 v53, a13
	v_accvgpr_read_b32 v52, a12
	v_accvgpr_read_b32 v50, a18
	v_accvgpr_read_b32 v49, a17
	v_accvgpr_read_b32 v48, a16
	s_add_i32 s30, s26, 26
	v_readlane_b32 s28, v100, s30
	s_nop 1
	v_mad_i64_i32 v[136:137], s[12:13], s28, v130, v[96:97]
	global_load_dwordx4 a[12:15], v[136:137], off
	v_mad_i64_i32 v[136:137], s[12:13], s28, v130, v[98:99]
	global_load_dwordx2 a[62:63], v[136:137], off
	s_add_i32 s30, s26, 27
	v_readlane_b32 s28, v100, s30
	s_nop 1
	v_mad_i64_i32 v[136:137], s[12:13], s28, v130, v[96:97]
	global_load_dwordx4 a[16:19], v[136:137], off
	v_mad_i64_i32 v[136:137], s[12:13], s28, v130, v[98:99]
	global_load_dwordx2 a[64:65], v[136:137], off
	s_waitcnt vmcnt(28)
	v_accvgpr_read_b32 v179, a67
	v_accvgpr_read_b32 v47, a27
	v_mov_b64_e32 v[40:41], v[220:221]
	v_accvgpr_read_b32 v178, a66
	v_mov_b64_e32 v[176:177], v[148:149]
	v_accvgpr_read_b32 v46, a26
	v_accvgpr_read_b32 v45, a25
	v_accvgpr_read_b32 v44, a24
	v_mov_b64_e32 v[42:43], v[222:223]
	s_add_i32 s30, s26, 28
	v_readlane_b32 s28, v100, s30
	s_nop 1
	v_mad_i64_i32 v[136:137], s[12:13], s28, v130, v[96:97]
	global_load_dwordx4 a[24:27], v[136:137], off
	v_mad_i64_i32 v[136:137], s[12:13], s28, v130, v[98:99]
	global_load_dwordx2 a[66:67], v[136:137], off
	s_add_i32 s30, s26, 29
	v_readlane_b32 s28, v100, s30
	s_nop 1
	v_mad_i64_i32 v[136:137], s[12:13], s28, v130, v[96:97]
	global_load_dwordx4 v[220:223], v[136:137], off
	v_mad_i64_i32 v[136:137], s[12:13], s28, v130, v[98:99]
	global_load_dwordx2 v[148:149], v[136:137], off
	s_waitcnt vmcnt(28)
	v_accvgpr_read_b32 v173, a41
	v_mov_b64_e32 v[36:37], v[224:225]
	v_mov_b64_e32 v[32:33], v[228:229]
	v_mov_b64_e32 v[174:175], v[252:253]
	v_accvgpr_read_b32 v172, a40
	v_mov_b64_e32 v[38:39], v[226:227]
	v_mov_b64_e32 v[34:35], v[230:231]
	s_add_i32 s30, s26, 30
	v_readlane_b32 s28, v100, s30
	s_nop 1
	v_mad_i64_i32 v[136:137], s[12:13], s28, v130, v[96:97]
	global_load_dwordx4 v[224:227], v[136:137], off
	v_mad_i64_i32 v[136:137], s[12:13], s28, v130, v[98:99]
	global_load_dwordx2 v[252:253], v[136:137], off
	s_add_i32 s30, s26, 31
	v_readlane_b32 s28, v100, s30
	s_nop 1
	v_mad_i64_i32 v[136:137], s[12:13], s28, v130, v[96:97]
	global_load_dwordx4 v[228:231], v[136:137], off
	v_mad_i64_i32 v[136:137], s[12:13], s28, v130, v[98:99]
	global_load_dwordx2 a[40:41], v[136:137], off
	s_cmp_lg_u32 s26, 64
	s_cbranch_scc1 .LBB0_1389
	global_load_dword a68, v[170:171], off
	global_load_dword a69, v[168:169], off
	global_load_dword v117, v[166:167], off
	global_load_dword v105, v[164:165], off
	s_branch .LBB0_1389

.LBB0_2102:
	s_andn2_saveexec_b64 s[50:51], s[50:51]
	v_mul_f32_e32 v34, v33, v33
	v_fmamk_f32 v35, v34, 0xba1345e1, v139
	v_fmaak_f32 v35, v34, v35, 0xbcdac9b8
	v_fmaak_f32 v35, v34, v35, 0x3de703be
	v_fmaak_f32 v35, v34, v35, 0xbec09330
	v_fmaak_f32 v34, v34, v35, 0x3e0375d0
	v_fma_f32 v34, |v33|, v34, |v33|
	s_or_b64 exec, exec, s[50:51]
	v_cvt_scalef32_pk_f32_fp4 v[36:37], v202, 1.0
	v_pk_fma_f32 v[36:37], s[30:31], v[36:37], v[198:199] op_sel_hi:[0,1,1]
	v_cvt_scalef32_pk_f32_fp4 v[38:39], v202, 1.0 op_sel:[1,0,0]
	v_cvt_scalef32_pk_f32_fp4 v[52:53], v200, 1.0
	v_pk_fma_f32 v[38:39], s[30:31], v[38:39], v[216:217] op_sel_hi:[0,1,1]
	v_cvt_scalef32_pk_f32_fp4 v[40:41], v202, 1.0 op_sel:[0,1,0]
	v_pk_fma_f32 v[36:37], s[28:29], v[52:53], v[36:37] op_sel_hi:[0,1,1]
	v_cvt_scalef32_pk_f32_fp4 v[52:53], v200, 1.0 op_sel:[1,0,0]
	v_pk_fma_f32 v[40:41], s[30:31], v[40:41], v[214:215] op_sel_hi:[0,1,1]
	v_cvt_scalef32_pk_f32_fp4 v[42:43], v202, 1.0 op_sel:[1,1,0]
	v_pk_fma_f32 v[38:39], s[28:29], v[52:53], v[38:39] op_sel_hi:[0,1,1]
	v_cvt_scalef32_pk_f32_fp4 v[52:53], v200, 1.0 op_sel:[0,1,0]
	v_pk_fma_f32 v[42:43], s[30:31], v[42:43], v[212:213] op_sel_hi:[0,1,1]
	v_cvt_scalef32_pk_f32_fp4 v[44:45], v203, 1.0
	v_pk_fma_f32 v[40:41], s[28:29], v[52:53], v[40:41] op_sel_hi:[0,1,1]
	v_cvt_scalef32_pk_f32_fp4 v[52:53], v200, 1.0 op_sel:[1,1,0]
	v_pk_fma_f32 v[44:45], s[30:31], v[44:45], v[210:211] op_sel_hi:[0,1,1]
	v_cvt_scalef32_pk_f32_fp4 v[46:47], v203, 1.0 op_sel:[1,0,0]
	v_pk_fma_f32 v[42:43], s[28:29], v[52:53], v[42:43] op_sel_hi:[0,1,1]
	v_cvt_scalef32_pk_f32_fp4 v[52:53], v201, 1.0
	v_pk_fma_f32 v[46:47], s[30:31], v[46:47], v[208:209] op_sel_hi:[0,1,1]
	v_cvt_scalef32_pk_f32_fp4 v[48:49], v203, 1.0 op_sel:[0,1,0]
	v_pk_fma_f32 v[44:45], s[28:29], v[52:53], v[44:45] op_sel_hi:[0,1,1]
	v_cvt_scalef32_pk_f32_fp4 v[52:53], v201, 1.0 op_sel:[1,0,0]
	v_pk_fma_f32 v[48:49], s[30:31], v[48:49], v[206:207] op_sel_hi:[0,1,1]
	v_cvt_scalef32_pk_f32_fp4 v[50:51], v203, 1.0 op_sel:[1,1,0]
	v_pk_fma_f32 v[46:47], s[28:29], v[52:53], v[46:47] op_sel_hi:[0,1,1]
	v_cvt_scalef32_pk_f32_fp4 v[52:53], v201, 1.0 op_sel:[0,1,0]
	v_pk_fma_f32 v[50:51], s[30:31], v[50:51], v[204:205] op_sel_hi:[0,1,1]
	v_pk_fma_f32 v[48:49], s[28:29], v[52:53], v[48:49] op_sel_hi:[0,1,1]
	v_cvt_scalef32_pk_f32_fp4 v[52:53], v201, 1.0 op_sel:[1,1,0]
	v_pk_fma_f32 v[50:51], s[28:29], v[52:53], v[50:51] op_sel_hi:[0,1,1]
	v_cvt_scalef32_pk_f32_fp4 v[52:53], v196, 1.0
	v_pk_fma_f32 v[36:37], s[26:27], v[52:53], v[36:37] op_sel_hi:[0,1,1]
	v_cvt_scalef32_pk_f32_fp4 v[52:53], v196, 1.0 op_sel:[1,0,0]
	v_pk_fma_f32 v[38:39], s[26:27], v[52:53], v[38:39] op_sel_hi:[0,1,1]
	v_cvt_scalef32_pk_f32_fp4 v[52:53], v196, 1.0 op_sel:[0,1,0]
	v_pk_fma_f32 v[40:41], s[26:27], v[52:53], v[40:41] op_sel_hi:[0,1,1]
	v_cvt_scalef32_pk_f32_fp4 v[52:53], v196, 1.0 op_sel:[1,1,0]
	v_pk_fma_f32 v[42:43], s[26:27], v[52:53], v[42:43] op_sel_hi:[0,1,1]
	v_cvt_scalef32_pk_f32_fp4 v[52:53], v197, 1.0
	v_pk_fma_f32 v[44:45], s[26:27], v[52:53], v[44:45] op_sel_hi:[0,1,1]
	v_cvt_scalef32_pk_f32_fp4 v[52:53], v197, 1.0 op_sel:[1,0,0]
	v_pk_fma_f32 v[46:47], s[26:27], v[52:53], v[46:47] op_sel_hi:[0,1,1]
	v_cvt_scalef32_pk_f32_fp4 v[52:53], v197, 1.0 op_sel:[0,1,0]
	v_pk_fma_f32 v[48:49], s[26:27], v[52:53], v[48:49] op_sel_hi:[0,1,1]
	v_cvt_scalef32_pk_f32_fp4 v[52:53], v197, 1.0 op_sel:[1,1,0]
	v_pk_fma_f32 v[50:51], s[26:27], v[52:53], v[50:51] op_sel_hi:[0,1,1]
	v_cvt_scalef32_pk_f32_fp4 v[52:53], v194, 1.0
	v_pk_fma_f32 v[36:37], s[12:13], v[52:53], v[36:37] op_sel_hi:[0,1,1]
	v_cvt_scalef32_pk_f32_fp4 v[52:53], v194, 1.0 op_sel:[1,0,0]
	v_pk_fma_f32 v[38:39], s[12:13], v[52:53], v[38:39] op_sel_hi:[0,1,1]
	v_cvt_scalef32_pk_f32_fp4 v[52:53], v194, 1.0 op_sel:[0,1,0]
	v_pk_fma_f32 v[40:41], s[12:13], v[52:53], v[40:41] op_sel_hi:[0,1,1]
	v_cvt_scalef32_pk_f32_fp4 v[52:53], v194, 1.0 op_sel:[1,1,0]
	v_pk_fma_f32 v[42:43], s[12:13], v[52:53], v[42:43] op_sel_hi:[0,1,1]
	v_cvt_scalef32_pk_f32_fp4 v[52:53], v195, 1.0
	v_pk_fma_f32 v[44:45], s[12:13], v[52:53], v[44:45] op_sel_hi:[0,1,1]
	v_cvt_scalef32_pk_f32_fp4 v[52:53], v195, 1.0 op_sel:[1,0,0]
	v_pk_fma_f32 v[46:47], s[12:13], v[52:53], v[46:47] op_sel_hi:[0,1,1]
	v_cvt_scalef32_pk_f32_fp4 v[52:53], v195, 1.0 op_sel:[0,1,0]
	v_pk_fma_f32 v[48:49], s[12:13], v[52:53], v[48:49] op_sel_hi:[0,1,1]
	v_cvt_scalef32_pk_f32_fp4 v[52:53], v195, 1.0 op_sel:[1,1,0]
	v_pk_fma_f32 v[50:51], s[12:13], v[52:53], v[50:51] op_sel_hi:[0,1,1]
	v_cvt_scalef32_pk_f32_fp4 v[52:53], v192, 1.0
	v_pk_fma_f32 v[36:37], s[40:41], v[52:53], v[36:37] op_sel_hi:[0,1,1]
	v_cvt_scalef32_pk_f32_fp4 v[52:53], v192, 1.0 op_sel:[1,0,0]
	v_pk_fma_f32 v[38:39], s[40:41], v[52:53], v[38:39] op_sel_hi:[0,1,1]
	v_cvt_scalef32_pk_f32_fp4 v[52:53], v192, 1.0 op_sel:[0,1,0]
	v_pk_fma_f32 v[40:41], s[40:41], v[52:53], v[40:41] op_sel_hi:[0,1,1]
	v_cvt_scalef32_pk_f32_fp4 v[52:53], v192, 1.0 op_sel:[1,1,0]
	v_pk_fma_f32 v[42:43], s[40:41], v[52:53], v[42:43] op_sel_hi:[0,1,1]
	v_cvt_scalef32_pk_f32_fp4 v[52:53], v193, 1.0
	v_pk_fma_f32 v[44:45], s[40:41], v[52:53], v[44:45] op_sel_hi:[0,1,1]
	v_cvt_scalef32_pk_f32_fp4 v[52:53], v193, 1.0 op_sel:[1,0,0]
	v_pk_fma_f32 v[46:47], s[40:41], v[52:53], v[46:47] op_sel_hi:[0,1,1]
	v_cvt_scalef32_pk_f32_fp4 v[52:53], v193, 1.0 op_sel:[0,1,0]
	v_pk_fma_f32 v[48:49], s[40:41], v[52:53], v[48:49] op_sel_hi:[0,1,1]
	v_cvt_scalef32_pk_f32_fp4 v[52:53], v193, 1.0 op_sel:[1,1,0]
	v_pk_fma_f32 v[50:51], s[40:41], v[52:53], v[50:51] op_sel_hi:[0,1,1]
	v_cvt_scalef32_pk_f32_fp4 v[52:53], v190, 1.0
	v_pk_fma_f32 v[36:37], s[38:39], v[52:53], v[36:37] op_sel_hi:[0,1,1]
	v_cvt_scalef32_pk_f32_fp4 v[52:53], v190, 1.0 op_sel:[1,0,0]
	v_pk_fma_f32 v[38:39], s[38:39], v[52:53], v[38:39] op_sel_hi:[0,1,1]
	v_cvt_scalef32_pk_f32_fp4 v[52:53], v190, 1.0 op_sel:[0,1,0]
	v_pk_fma_f32 v[40:41], s[38:39], v[52:53], v[40:41] op_sel_hi:[0,1,1]
	v_cvt_scalef32_pk_f32_fp4 v[52:53], v190, 1.0 op_sel:[1,1,0]
	v_pk_fma_f32 v[42:43], s[38:39], v[52:53], v[42:43] op_sel_hi:[0,1,1]
	v_cvt_scalef32_pk_f32_fp4 v[52:53], v191, 1.0
	v_pk_fma_f32 v[44:45], s[38:39], v[52:53], v[44:45] op_sel_hi:[0,1,1]
	v_cvt_scalef32_pk_f32_fp4 v[52:53], v191, 1.0 op_sel:[1,0,0]
	v_pk_fma_f32 v[46:47], s[38:39], v[52:53], v[46:47] op_sel_hi:[0,1,1]
	v_cvt_scalef32_pk_f32_fp4 v[52:53], v191, 1.0 op_sel:[0,1,0]
	v_pk_fma_f32 v[48:49], s[38:39], v[52:53], v[48:49] op_sel_hi:[0,1,1]
	v_cvt_scalef32_pk_f32_fp4 v[52:53], v191, 1.0 op_sel:[1,1,0]
	v_pk_fma_f32 v[50:51], s[38:39], v[52:53], v[50:51] op_sel_hi:[0,1,1]
	v_cvt_scalef32_pk_f32_fp4 v[52:53], v188, 1.0
	v_pk_fma_f32 v[36:37], s[36:37], v[52:53], v[36:37] op_sel_hi:[0,1,1]
	v_cvt_scalef32_pk_f32_fp4 v[52:53], v188, 1.0 op_sel:[1,0,0]
	v_pk_fma_f32 v[38:39], s[36:37], v[52:53], v[38:39] op_sel_hi:[0,1,1]
	v_cvt_scalef32_pk_f32_fp4 v[52:53], v188, 1.0 op_sel:[0,1,0]
	v_pk_fma_f32 v[40:41], s[36:37], v[52:53], v[40:41] op_sel_hi:[0,1,1]
	v_cvt_scalef32_pk_f32_fp4 v[52:53], v188, 1.0 op_sel:[1,1,0]
	v_pk_fma_f32 v[42:43], s[36:37], v[52:53], v[42:43] op_sel_hi:[0,1,1]
	v_cvt_scalef32_pk_f32_fp4 v[52:53], v189, 1.0
	v_pk_fma_f32 v[44:45], s[36:37], v[52:53], v[44:45] op_sel_hi:[0,1,1]
	v_cvt_scalef32_pk_f32_fp4 v[52:53], v189, 1.0 op_sel:[1,0,0]
	v_pk_fma_f32 v[46:47], s[36:37], v[52:53], v[46:47] op_sel_hi:[0,1,1]
	v_cvt_scalef32_pk_f32_fp4 v[52:53], v189, 1.0 op_sel:[0,1,0]
	v_pk_fma_f32 v[48:49], s[36:37], v[52:53], v[48:49] op_sel_hi:[0,1,1]
	v_cvt_scalef32_pk_f32_fp4 v[52:53], v189, 1.0 op_sel:[1,1,0]
	v_pk_fma_f32 v[50:51], s[36:37], v[52:53], v[50:51] op_sel_hi:[0,1,1]
	v_cvt_scalef32_pk_f32_fp4 v[52:53], v186, 1.0
	v_pk_fma_f32 v[36:37], s[34:35], v[52:53], v[36:37] op_sel_hi:[0,1,1]
	v_cvt_scalef32_pk_f32_fp4 v[52:53], v186, 1.0 op_sel:[1,0,0]
	v_pk_fma_f32 v[38:39], s[34:35], v[52:53], v[38:39] op_sel_hi:[0,1,1]
	v_cvt_scalef32_pk_f32_fp4 v[52:53], v186, 1.0 op_sel:[0,1,0]
	v_pk_fma_f32 v[40:41], s[34:35], v[52:53], v[40:41] op_sel_hi:[0,1,1]
	v_cvt_scalef32_pk_f32_fp4 v[52:53], v186, 1.0 op_sel:[1,1,0]
	v_pk_fma_f32 v[42:43], s[34:35], v[52:53], v[42:43] op_sel_hi:[0,1,1]
	v_cvt_scalef32_pk_f32_fp4 v[52:53], v187, 1.0
	v_pk_fma_f32 v[44:45], s[34:35], v[52:53], v[44:45] op_sel_hi:[0,1,1]
	v_cvt_scalef32_pk_f32_fp4 v[52:53], v187, 1.0 op_sel:[1,0,0]
	v_pk_fma_f32 v[46:47], s[34:35], v[52:53], v[46:47] op_sel_hi:[0,1,1]
	v_cvt_scalef32_pk_f32_fp4 v[52:53], v187, 1.0 op_sel:[0,1,0]
	v_pk_fma_f32 v[48:49], s[34:35], v[52:53], v[48:49] op_sel_hi:[0,1,1]
	v_cvt_scalef32_pk_f32_fp4 v[52:53], v187, 1.0 op_sel:[1,1,0]
	v_pk_fma_f32 v[50:51], s[34:35], v[52:53], v[50:51] op_sel_hi:[0,1,1]
	v_cvt_scalef32_pk_f32_fp4 v[52:53], v184, 1.0
	v_pk_fma_f32 v[36:37], s[48:49], v[52:53], v[36:37] op_sel_hi:[0,1,1]
	v_cvt_scalef32_pk_f32_fp4 v[52:53], v184, 1.0 op_sel:[1,0,0]
	v_pk_fma_f32 v[38:39], s[48:49], v[52:53], v[38:39] op_sel_hi:[0,1,1]
	v_cvt_scalef32_pk_f32_fp4 v[52:53], v184, 1.0 op_sel:[0,1,0]
	v_pk_fma_f32 v[40:41], s[48:49], v[52:53], v[40:41] op_sel_hi:[0,1,1]
	v_cvt_scalef32_pk_f32_fp4 v[52:53], v184, 1.0 op_sel:[1,1,0]
	v_pk_fma_f32 v[42:43], s[48:49], v[52:53], v[42:43] op_sel_hi:[0,1,1]
	v_cvt_scalef32_pk_f32_fp4 v[52:53], v185, 1.0
	v_pk_fma_f32 v[44:45], s[48:49], v[52:53], v[44:45] op_sel_hi:[0,1,1]
	v_cvt_scalef32_pk_f32_fp4 v[52:53], v185, 1.0 op_sel:[1,0,0]
	v_pk_fma_f32 v[46:47], s[48:49], v[52:53], v[46:47] op_sel_hi:[0,1,1]
	v_cvt_scalef32_pk_f32_fp4 v[52:53], v185, 1.0 op_sel:[0,1,0]
	v_pk_fma_f32 v[48:49], s[48:49], v[52:53], v[48:49] op_sel_hi:[0,1,1]
	v_cvt_scalef32_pk_f32_fp4 v[52:53], v185, 1.0 op_sel:[1,1,0]
	v_pk_fma_f32 v[50:51], s[48:49], v[52:53], v[50:51] op_sel_hi:[0,1,1]
	v_cvt_scalef32_pk_f32_fp4 v[52:53], v182, 1.0
	v_pk_fma_f32 v[36:37], s[46:47], v[52:53], v[36:37] op_sel_hi:[0,1,1]
	v_cvt_scalef32_pk_f32_fp4 v[52:53], v182, 1.0 op_sel:[1,0,0]
	v_pk_fma_f32 v[38:39], s[46:47], v[52:53], v[38:39] op_sel_hi:[0,1,1]
	v_cvt_scalef32_pk_f32_fp4 v[52:53], v182, 1.0 op_sel:[0,1,0]
	v_pk_fma_f32 v[40:41], s[46:47], v[52:53], v[40:41] op_sel_hi:[0,1,1]
	v_cvt_scalef32_pk_f32_fp4 v[52:53], v182, 1.0 op_sel:[1,1,0]
	v_pk_fma_f32 v[42:43], s[46:47], v[52:53], v[42:43] op_sel_hi:[0,1,1]
	v_cvt_scalef32_pk_f32_fp4 v[52:53], v183, 1.0
	v_pk_fma_f32 v[44:45], s[46:47], v[52:53], v[44:45] op_sel_hi:[0,1,1]
	v_cvt_scalef32_pk_f32_fp4 v[52:53], v183, 1.0 op_sel:[1,0,0]
	v_pk_fma_f32 v[46:47], s[46:47], v[52:53], v[46:47] op_sel_hi:[0,1,1]
	v_cvt_scalef32_pk_f32_fp4 v[52:53], v183, 1.0 op_sel:[0,1,0]
	v_pk_fma_f32 v[48:49], s[46:47], v[52:53], v[48:49] op_sel_hi:[0,1,1]
	v_cvt_scalef32_pk_f32_fp4 v[52:53], v183, 1.0 op_sel:[1,1,0]
	v_pk_fma_f32 v[50:51], s[46:47], v[52:53], v[50:51] op_sel_hi:[0,1,1]
	v_cvt_scalef32_pk_f32_fp4 v[52:53], v180, 1.0
	v_pk_fma_f32 v[36:37], s[44:45], v[52:53], v[36:37] op_sel_hi:[0,1,1]
	v_cvt_scalef32_pk_f32_fp4 v[52:53], v180, 1.0 op_sel:[1,0,0]
	v_pk_fma_f32 v[38:39], s[44:45], v[52:53], v[38:39] op_sel_hi:[0,1,1]
	v_cvt_scalef32_pk_f32_fp4 v[52:53], v180, 1.0 op_sel:[0,1,0]
	v_pk_fma_f32 v[40:41], s[44:45], v[52:53], v[40:41] op_sel_hi:[0,1,1]
	v_cvt_scalef32_pk_f32_fp4 v[52:53], v180, 1.0 op_sel:[1,1,0]
	v_pk_fma_f32 v[42:43], s[44:45], v[52:53], v[42:43] op_sel_hi:[0,1,1]
	v_cvt_scalef32_pk_f32_fp4 v[52:53], v181, 1.0
	v_pk_fma_f32 v[44:45], s[44:45], v[52:53], v[44:45] op_sel_hi:[0,1,1]
	v_cvt_scalef32_pk_f32_fp4 v[52:53], v181, 1.0 op_sel:[1,0,0]
	v_pk_fma_f32 v[46:47], s[44:45], v[52:53], v[46:47] op_sel_hi:[0,1,1]
	v_cvt_scalef32_pk_f32_fp4 v[52:53], v181, 1.0 op_sel:[0,1,0]
	v_pk_fma_f32 v[48:49], s[44:45], v[52:53], v[48:49] op_sel_hi:[0,1,1]
	v_cvt_scalef32_pk_f32_fp4 v[52:53], v181, 1.0 op_sel:[1,1,0]
	v_pk_fma_f32 v[50:51], s[44:45], v[52:53], v[50:51] op_sel_hi:[0,1,1]
	v_cvt_scalef32_pk_f32_fp4 v[52:53], v178, 1.0
	v_pk_fma_f32 v[36:37], s[42:43], v[52:53], v[36:37] op_sel_hi:[0,1,1]
	v_cvt_scalef32_pk_f32_fp4 v[52:53], v178, 1.0 op_sel:[1,0,0]
	v_pk_fma_f32 v[38:39], s[42:43], v[52:53], v[38:39] op_sel_hi:[0,1,1]
	v_cvt_scalef32_pk_f32_fp4 v[52:53], v178, 1.0 op_sel:[0,1,0]
	v_pk_fma_f32 v[40:41], s[42:43], v[52:53], v[40:41] op_sel_hi:[0,1,1]
	v_cvt_scalef32_pk_f32_fp4 v[52:53], v178, 1.0 op_sel:[1,1,0]
	v_pk_fma_f32 v[42:43], s[42:43], v[52:53], v[42:43] op_sel_hi:[0,1,1]
	v_cvt_scalef32_pk_f32_fp4 v[52:53], v179, 1.0
	v_pk_fma_f32 v[44:45], s[42:43], v[52:53], v[44:45] op_sel_hi:[0,1,1]
	v_cvt_scalef32_pk_f32_fp4 v[52:53], v179, 1.0 op_sel:[1,0,0]
	v_pk_fma_f32 v[46:47], s[42:43], v[52:53], v[46:47] op_sel_hi:[0,1,1]
	v_cvt_scalef32_pk_f32_fp4 v[52:53], v179, 1.0 op_sel:[0,1,0]
	v_pk_fma_f32 v[48:49], s[42:43], v[52:53], v[48:49] op_sel_hi:[0,1,1]
	v_cvt_scalef32_pk_f32_fp4 v[52:53], v179, 1.0 op_sel:[1,1,0]
	v_pk_fma_f32 v[50:51], s[42:43], v[52:53], v[50:51] op_sel_hi:[0,1,1]
	v_mov_b32_e32 v35, s59
	v_mov_b32_e32 v52, s35
	v_cndmask_b32_e64 v35, v35, v52, s[10:11]
	v_mov_b32_e32 v52, s43
	v_bfi_b32 v33, s55, v34, v33
	v_cndmask_b32_e64 v35, v35, v52, s[8:9]
	v_mov_b32_e32 v52, s13
	v_mul_f32_e32 v32, 0.5, v32
	v_add_f32_e32 v33, 1.0, v33
	v_cndmask_b32_e64 v35, v35, v52, s[6:7]
	v_mul_f32_e32 v32, v32, v33
	v_mul_f32_e32 v32, v35, v32
	v_cvt_scalef32_pk_f32_fp4 v[34:35], v176, 1.0 op_sel:[1,0,0]
	v_readlane_b32 s12, v32, 0
	v_readlane_b32 s26, v32, 32
	v_readlane_b32 s28, v32, 16
	v_readlane_b32 s30, v32, 48
	v_cvt_scalef32_pk_f32_fp4 v[32:33], v176, 1.0
	v_pk_fma_f32 v[32:33], s[12:13], v[32:33], v[36:37] op_sel_hi:[0,1,1]
	v_cvt_scalef32_pk_f32_fp4 v[36:37], v176, 1.0 op_sel:[0,1,0]
	v_pk_fma_f32 v[36:37], s[12:13], v[36:37], v[40:41] op_sel_hi:[0,1,1]
	v_cvt_scalef32_pk_f32_fp4 v[40:41], v177, 1.0
	v_pk_fma_f32 v[40:41], s[12:13], v[40:41], v[44:45] op_sel_hi:[0,1,1]
	v_cvt_scalef32_pk_f32_fp4 v[44:45], v177, 1.0 op_sel:[0,1,0]
	v_pk_fma_f32 v[44:45], s[12:13], v[44:45], v[48:49] op_sel_hi:[0,1,1]
	v_cvt_scalef32_pk_f32_fp4 v[48:49], v174, 1.0
	v_pk_fma_f32 v[34:35], s[12:13], v[34:35], v[38:39] op_sel_hi:[0,1,1]
	v_pk_fma_f32 v[32:33], s[26:27], v[48:49], v[32:33] op_sel_hi:[0,1,1]
	v_cvt_scalef32_pk_f32_fp4 v[48:49], v174, 1.0 op_sel:[1,0,0]
	v_cvt_scalef32_pk_f32_fp4 v[38:39], v176, 1.0 op_sel:[1,1,0]
	v_pk_fma_f32 v[34:35], s[26:27], v[48:49], v[34:35] op_sel_hi:[0,1,1]
	v_cvt_scalef32_pk_f32_fp4 v[48:49], v174, 1.0 op_sel:[0,1,0]
	v_pk_fma_f32 v[38:39], s[12:13], v[38:39], v[42:43] op_sel_hi:[0,1,1]
	v_pk_fma_f32 v[36:37], s[26:27], v[48:49], v[36:37] op_sel_hi:[0,1,1]
	v_cvt_scalef32_pk_f32_fp4 v[48:49], v174, 1.0 op_sel:[1,1,0]
	v_cvt_scalef32_pk_f32_fp4 v[42:43], v177, 1.0 op_sel:[1,0,0]
	v_pk_fma_f32 v[38:39], s[26:27], v[48:49], v[38:39] op_sel_hi:[0,1,1]
	v_cvt_scalef32_pk_f32_fp4 v[48:49], v175, 1.0
	v_pk_fma_f32 v[42:43], s[12:13], v[42:43], v[46:47] op_sel_hi:[0,1,1]
	v_pk_fma_f32 v[40:41], s[26:27], v[48:49], v[40:41] op_sel_hi:[0,1,1]
	v_cvt_scalef32_pk_f32_fp4 v[48:49], v175, 1.0 op_sel:[1,0,0]
	v_cvt_scalef32_pk_f32_fp4 v[46:47], v177, 1.0 op_sel:[1,1,0]
	v_pk_fma_f32 v[42:43], s[26:27], v[48:49], v[42:43] op_sel_hi:[0,1,1]
	v_cvt_scalef32_pk_f32_fp4 v[48:49], v175, 1.0 op_sel:[0,1,0]
	v_pk_fma_f32 v[46:47], s[12:13], v[46:47], v[50:51] op_sel_hi:[0,1,1]
	v_pk_fma_f32 v[44:45], s[26:27], v[48:49], v[44:45] op_sel_hi:[0,1,1]
	v_cvt_scalef32_pk_f32_fp4 v[48:49], v175, 1.0 op_sel:[1,1,0]
	v_pk_fma_f32 v[46:47], s[26:27], v[48:49], v[46:47] op_sel_hi:[0,1,1]
	v_cvt_scalef32_pk_f32_fp4 v[48:49], v172, 1.0
	v_pk_fma_f32 v[32:33], s[28:29], v[48:49], v[32:33] op_sel_hi:[0,1,1]
	v_cvt_scalef32_pk_f32_fp4 v[48:49], v172, 1.0 op_sel:[1,0,0]
	v_pk_fma_f32 v[34:35], s[28:29], v[48:49], v[34:35] op_sel_hi:[0,1,1]
	v_cvt_scalef32_pk_f32_fp4 v[48:49], v172, 1.0 op_sel:[0,1,0]
	v_pk_fma_f32 v[36:37], s[28:29], v[48:49], v[36:37] op_sel_hi:[0,1,1]
	v_cvt_scalef32_pk_f32_fp4 v[48:49], v172, 1.0 op_sel:[1,1,0]
	v_pk_fma_f32 v[38:39], s[28:29], v[48:49], v[38:39] op_sel_hi:[0,1,1]
	v_cvt_scalef32_pk_f32_fp4 v[48:49], v173, 1.0
	v_pk_fma_f32 v[40:41], s[28:29], v[48:49], v[40:41] op_sel_hi:[0,1,1]
	v_cvt_scalef32_pk_f32_fp4 v[48:49], v173, 1.0 op_sel:[1,0,0]
	v_pk_fma_f32 v[42:43], s[28:29], v[48:49], v[42:43] op_sel_hi:[0,1,1]
	v_cvt_scalef32_pk_f32_fp4 v[48:49], v173, 1.0 op_sel:[0,1,0]
	v_pk_fma_f32 v[44:45], s[28:29], v[48:49], v[44:45] op_sel_hi:[0,1,1]
	v_cvt_scalef32_pk_f32_fp4 v[48:49], v173, 1.0 op_sel:[1,1,0]
	v_pk_fma_f32 v[46:47], s[28:29], v[48:49], v[46:47] op_sel_hi:[0,1,1]
	v_cvt_scalef32_pk_f32_fp4 v[48:49], v170, 1.0
	v_pk_fma_f32 v[198:199], s[30:31], v[48:49], v[32:33] op_sel_hi:[0,1,1]
	v_cvt_scalef32_pk_f32_fp4 v[32:33], v170, 1.0 op_sel:[1,0,0]
	v_pk_fma_f32 v[216:217], s[30:31], v[32:33], v[34:35] op_sel_hi:[0,1,1]
	v_cvt_scalef32_pk_f32_fp4 v[32:33], v170, 1.0 op_sel:[0,1,0]
	v_pk_fma_f32 v[214:215], s[30:31], v[32:33], v[36:37] op_sel_hi:[0,1,1]
	v_cvt_scalef32_pk_f32_fp4 v[32:33], v170, 1.0 op_sel:[1,1,0]
	v_pk_fma_f32 v[212:213], s[30:31], v[32:33], v[38:39] op_sel_hi:[0,1,1]
	v_cvt_scalef32_pk_f32_fp4 v[32:33], v171, 1.0
	v_pk_fma_f32 v[210:211], s[30:31], v[32:33], v[40:41] op_sel_hi:[0,1,1]
	v_cvt_scalef32_pk_f32_fp4 v[32:33], v171, 1.0 op_sel:[1,0,0]
	v_pk_fma_f32 v[208:209], s[30:31], v[32:33], v[42:43] op_sel_hi:[0,1,1]
	v_cvt_scalef32_pk_f32_fp4 v[32:33], v171, 1.0 op_sel:[0,1,0]
	v_pk_fma_f32 v[206:207], s[30:31], v[32:33], v[44:45] op_sel_hi:[0,1,1]
	v_cvt_scalef32_pk_f32_fp4 v[32:33], v171, 1.0 op_sel:[1,1,0]
	v_pk_fma_f32 v[204:205], s[30:31], v[32:33], v[46:47] op_sel_hi:[0,1,1]
	s_and_b64 vcc, exec, s[24:25]
	s_cbranch_vccnz .LBB0_2084
	s_mov_b32 s26, s58
	s_add_i32 s58, s26, 16
	s_cmpk_gt_u32 s26, 0x6f
	s_cselect_b64 s[24:25], -1, 0
	s_cmpk_lt_u32 s26, 0x70
	s_cselect_b64 vcc, -1, 0
	s_bitcmp0_b32 s58, 6
	s_cselect_b64 s[12:13], -1, 0
	v_cndmask_b32_e64 v100, v116, v102, s[12:13]
	v_cndmask_b32_e32 v100, v118, v100, vcc
	s_nop 0
	s_waitcnt vmcnt(28)
	v_accvgpr_read_b32 v203, a43
	v_accvgpr_read_b32 v201, a45
	v_accvgpr_read_b32 v95, a23
	v_accvgpr_read_b32 v91, a27
	v_accvgpr_read_b32 v202, a42
	v_accvgpr_read_b32 v200, a44
	v_accvgpr_read_b32 v94, a22
	v_accvgpr_read_b32 v93, a21
	v_accvgpr_read_b32 v92, a20
	v_accvgpr_read_b32 v90, a26
	v_accvgpr_read_b32 v89, a25
	v_accvgpr_read_b32 v88, a24
	s_add_i32 s30, s26, 16
	v_readlane_b32 s28, v100, s30
	s_nop 1
	v_mad_i64_i32 v[136:137], s[12:13], s28, v130, v[96:97]
	global_load_dwordx4 a[20:23], v[136:137], off
	v_mad_i64_i32 v[136:137], s[12:13], s28, v130, v[98:99]
	global_load_dwordx2 a[42:43], v[136:137], off
	s_add_i32 s30, s26, 17
	v_readlane_b32 s28, v100, s30
	s_nop 1
	v_mad_i64_i32 v[136:137], s[12:13], s28, v130, v[96:97]
	global_load_dwordx4 a[24:27], v[136:137], off
	v_mad_i64_i32 v[136:137], s[12:13], s28, v130, v[98:99]
	global_load_dwordx2 a[44:45], v[136:137], off
	s_waitcnt vmcnt(28)
	v_accvgpr_read_b32 v197, a47
	v_accvgpr_read_b32 v195, a49
	v_mov_b64_e32 v[84:85], v[230:231]
	v_mov_b64_e32 v[80:81], v[234:235]
	v_accvgpr_read_b32 v196, a46
	v_accvgpr_read_b32 v194, a48
	v_mov_b64_e32 v[86:87], v[232:233]
	v_mov_b64_e32 v[82:83], v[236:237]
	s_add_i32 s30, s26, 18
	v_readlane_b32 s28, v100, s30
	s_nop 1
	v_mad_i64_i32 v[136:137], s[12:13], s28, v130, v[96:97]
	global_load_dwordx4 v[230:233], v[136:137], off
	v_mad_i64_i32 v[136:137], s[12:13], s28, v130, v[98:99]
	global_load_dwordx2 a[46:47], v[136:137], off
	s_add_i32 s30, s26, 19
	v_readlane_b32 s28, v100, s30
	s_nop 1
	v_mad_i64_i32 v[136:137], s[12:13], s28, v130, v[96:97]
	global_load_dwordx4 v[234:237], v[136:137], off
	v_mad_i64_i32 v[136:137], s[12:13], s28, v130, v[98:99]
	global_load_dwordx2 a[48:49], v[136:137], off
	s_waitcnt vmcnt(28)
	v_accvgpr_read_b32 v193, a51
	v_accvgpr_read_b32 v191, a53
	v_mov_b64_e32 v[76:77], v[238:239]
	v_mov_b64_e32 v[72:73], v[242:243]
	v_accvgpr_read_b32 v192, a50
	v_accvgpr_read_b32 v190, a52
	v_mov_b64_e32 v[78:79], v[240:241]
	v_mov_b64_e32 v[74:75], v[244:245]
	s_add_i32 s30, s26, 20
	v_readlane_b32 s28, v100, s30
	s_nop 1
	v_mad_i64_i32 v[136:137], s[12:13], s28, v130, v[96:97]
	global_load_dwordx4 v[238:241], v[136:137], off
	v_mad_i64_i32 v[136:137], s[12:13], s28, v130, v[98:99]
	global_load_dwordx2 a[50:51], v[136:137], off
	s_add_i32 s30, s26, 21
	v_readlane_b32 s28, v100, s30
	s_nop 1
	v_mad_i64_i32 v[136:137], s[12:13], s28, v130, v[96:97]
	global_load_dwordx4 v[242:245], v[136:137], off
	v_mad_i64_i32 v[136:137], s[12:13], s28, v130, v[98:99]
	global_load_dwordx2 a[52:53], v[136:137], off
	s_waitcnt vmcnt(28)
	v_accvgpr_read_b32 v189, a55
	v_accvgpr_read_b32 v187, a57
	v_mov_b64_e32 v[68:69], v[246:247]
	v_mov_b64_e32 v[64:65], v[250:251]
	v_accvgpr_read_b32 v188, a54
	v_accvgpr_read_b32 v186, a56
	v_mov_b64_e32 v[70:71], v[248:249]
	v_mov_b64_e32 v[66:67], v[252:253]
	s_add_i32 s30, s26, 22
	v_readlane_b32 s28, v100, s30
	s_nop 1
	v_mad_i64_i32 v[136:137], s[12:13], s28, v130, v[96:97]
	global_load_dwordx4 v[246:249], v[136:137], off
	v_mad_i64_i32 v[136:137], s[12:13], s28, v130, v[98:99]
	global_load_dwordx2 a[54:55], v[136:137], off
	s_add_i32 s30, s26, 23
	v_readlane_b32 s28, v100, s30
	s_nop 1
	v_mad_i64_i32 v[136:137], s[12:13], s28, v130, v[96:97]
	global_load_dwordx4 v[250:253], v[136:137], off
	v_mad_i64_i32 v[136:137], s[12:13], s28, v130, v[98:99]
	global_load_dwordx2 a[56:57], v[136:137], off
	s_waitcnt vmcnt(28)
	v_accvgpr_read_b32 v185, a59
	v_accvgpr_read_b32 v183, a61
	v_accvgpr_read_b32 v63, a3
	v_accvgpr_read_b32 v59, a7
	v_accvgpr_read_b32 v184, a58
	v_accvgpr_read_b32 v182, a60
	v_accvgpr_read_b32 v62, a2
	v_accvgpr_read_b32 v61, a1
	v_accvgpr_read_b32 v60, a0
	v_accvgpr_read_b32 v58, a6
	v_accvgpr_read_b32 v57, a5
	v_accvgpr_read_b32 v56, a4
	s_add_i32 s30, s26, 24
	v_readlane_b32 s28, v100, s30
	s_nop 1
	v_mad_i64_i32 v[136:137], s[12:13], s28, v130, v[96:97]
	global_load_dwordx4 a[0:3], v[136:137], off
	v_mad_i64_i32 v[136:137], s[12:13], s28, v130, v[98:99]
	global_load_dwordx2 a[58:59], v[136:137], off
	s_add_i32 s30, s26, 25
	v_readlane_b32 s28, v100, s30
	s_nop 1
	v_mad_i64_i32 v[136:137], s[12:13], s28, v130, v[96:97]
	global_load_dwordx4 a[4:7], v[136:137], off
	v_mad_i64_i32 v[136:137], s[12:13], s28, v130, v[98:99]
	global_load_dwordx2 a[60:61], v[136:137], off
	s_waitcnt vmcnt(28)
	v_accvgpr_read_b32 v181, a63
	v_accvgpr_read_b32 v179, a65
	v_accvgpr_read_b32 v55, a11
	v_accvgpr_read_b32 v51, a15
	v_accvgpr_read_b32 v180, a62
	v_accvgpr_read_b32 v178, a64
	v_accvgpr_read_b32 v54, a10
	v_accvgpr_read_b32 v53, a9
	v_accvgpr_read_b32 v52, a8
	v_accvgpr_read_b32 v50, a14
	v_accvgpr_read_b32 v49, a13
	v_accvgpr_read_b32 v48, a12
	s_add_i32 s30, s26, 26
	v_readlane_b32 s28, v100, s30
	s_nop 1
	v_mad_i64_i32 v[136:137], s[12:13], s28, v130, v[96:97]
	global_load_dwordx4 a[8:11], v[136:137], off
	v_mad_i64_i32 v[136:137], s[12:13], s28, v130, v[98:99]
	global_load_dwordx2 a[62:63], v[136:137], off
	s_add_i32 s30, s26, 27
	v_readlane_b32 s28, v100, s30
	s_nop 1
	v_mad_i64_i32 v[136:137], s[12:13], s28, v130, v[96:97]
	global_load_dwordx4 a[12:15], v[136:137], off
	v_mad_i64_i32 v[136:137], s[12:13], s28, v130, v[98:99]
	global_load_dwordx2 a[64:65], v[136:137], off
	s_waitcnt vmcnt(28)
	v_accvgpr_read_b32 v177, a67
	v_accvgpr_read_b32 v175, a37
	v_accvgpr_read_b32 v47, a19
	v_mov_b64_e32 v[40:41], v[218:219]
	v_accvgpr_read_b32 v176, a66
	v_accvgpr_read_b32 v174, a36
	v_accvgpr_read_b32 v46, a18
	v_accvgpr_read_b32 v45, a17
	v_accvgpr_read_b32 v44, a16
	v_mov_b64_e32 v[42:43], v[220:221]
	s_add_i32 s30, s26, 28
	v_readlane_b32 s28, v100, s30
	s_nop 1
	v_mad_i64_i32 v[136:137], s[12:13], s28, v130, v[96:97]
	global_load_dwordx4 a[16:19], v[136:137], off
	v_mad_i64_i32 v[136:137], s[12:13], s28, v130, v[98:99]
	global_load_dwordx2 a[66:67], v[136:137], off
	s_add_i32 s30, s26, 29
	v_readlane_b32 s28, v100, s30
	s_nop 1
	v_mad_i64_i32 v[136:137], s[12:13], s28, v130, v[96:97]
	global_load_dwordx4 v[218:221], v[136:137], off
	v_mad_i64_i32 v[136:137], s[12:13], s28, v130, v[98:99]
	global_load_dwordx2 a[36:37], v[136:137], off
	s_waitcnt vmcnt(28)
	v_accvgpr_read_b32 v173, a39
	v_accvgpr_read_b32 v171, a41
	v_mov_b64_e32 v[36:37], v[222:223]
	v_mov_b64_e32 v[32:33], v[226:227]
	v_accvgpr_read_b32 v172, a38
	v_accvgpr_read_b32 v170, a40
	v_mov_b64_e32 v[38:39], v[224:225]
	v_mov_b64_e32 v[34:35], v[228:229]
	s_add_i32 s30, s26, 30
	v_readlane_b32 s28, v100, s30
	s_nop 1
	v_mad_i64_i32 v[136:137], s[12:13], s28, v130, v[96:97]
	global_load_dwordx4 v[222:225], v[136:137], off
	v_mad_i64_i32 v[136:137], s[12:13], s28, v130, v[98:99]
	global_load_dwordx2 a[38:39], v[136:137], off
	s_add_i32 s30, s26, 31
	v_readlane_b32 s28, v100, s30
	s_nop 1
	v_mad_i64_i32 v[136:137], s[12:13], s28, v130, v[96:97]
	global_load_dwordx4 v[226:229], v[136:137], off
	v_mad_i64_i32 v[136:137], s[12:13], s28, v130, v[98:99]
	global_load_dwordx2 a[40:41], v[136:137], off
	s_cmp_lg_u32 s26, 64
	s_cbranch_scc1 .LBB0_2088
	global_load_dword a68, v[168:169], off
	global_load_dword a69, v[166:167], off
	global_load_dword v117, v[164:165], off
	global_load_dword v103, v[162:163], off
	s_branch .LBB0_2088

.LBB0_2587:
	s_andn2_saveexec_b64 s[42:43], s[42:43]
	v_mul_f32_e32 v34, v33, v33
	v_fmamk_f32 v35, v34, 0xba1345e1, v195
	v_fmaak_f32 v35, v34, v35, 0xbcdac9b8
	v_fmaak_f32 v35, v34, v35, 0x3de703be
	v_fmaak_f32 v35, v34, v35, 0xbec09330
	v_fmaak_f32 v34, v34, v35, 0x3e0375d0
	v_fma_f32 v34, |v33|, v34, |v33|
	s_or_b64 exec, exec, s[42:43]
	v_cvt_scalef32_pk_f32_fp4 v[36:37], v182, 1.0
	v_pk_fma_f32 v[36:37], s[22:23], v[36:37], v[174:175] op_sel_hi:[0,1,1]
	v_cvt_scalef32_pk_f32_fp4 v[38:39], v182, 1.0 op_sel:[1,0,0]
	v_cvt_scalef32_pk_f32_fp4 v[52:53], v176, 1.0
	v_pk_fma_f32 v[38:39], s[22:23], v[38:39], v[192:193] op_sel_hi:[0,1,1]
	v_cvt_scalef32_pk_f32_fp4 v[40:41], v182, 1.0 op_sel:[0,1,0]
	v_pk_fma_f32 v[36:37], s[20:21], v[52:53], v[36:37] op_sel_hi:[0,1,1]
	v_cvt_scalef32_pk_f32_fp4 v[52:53], v176, 1.0 op_sel:[1,0,0]
	v_pk_fma_f32 v[40:41], s[22:23], v[40:41], v[188:189] op_sel_hi:[0,1,1]
	v_cvt_scalef32_pk_f32_fp4 v[42:43], v182, 1.0 op_sel:[1,1,0]
	v_pk_fma_f32 v[38:39], s[20:21], v[52:53], v[38:39] op_sel_hi:[0,1,1]
	v_cvt_scalef32_pk_f32_fp4 v[52:53], v176, 1.0 op_sel:[0,1,0]
	v_pk_fma_f32 v[42:43], s[22:23], v[42:43], v[190:191] op_sel_hi:[0,1,1]
	v_cvt_scalef32_pk_f32_fp4 v[44:45], v183, 1.0
	v_pk_fma_f32 v[40:41], s[20:21], v[52:53], v[40:41] op_sel_hi:[0,1,1]
	v_cvt_scalef32_pk_f32_fp4 v[52:53], v176, 1.0 op_sel:[1,1,0]
	v_pk_fma_f32 v[44:45], s[22:23], v[44:45], v[184:185] op_sel_hi:[0,1,1]
	v_cvt_scalef32_pk_f32_fp4 v[46:47], v183, 1.0 op_sel:[1,0,0]
	v_pk_fma_f32 v[42:43], s[20:21], v[52:53], v[42:43] op_sel_hi:[0,1,1]
	v_cvt_scalef32_pk_f32_fp4 v[52:53], v177, 1.0
	v_pk_fma_f32 v[46:47], s[22:23], v[46:47], v[186:187] op_sel_hi:[0,1,1]
	v_cvt_scalef32_pk_f32_fp4 v[48:49], v183, 1.0 op_sel:[0,1,0]
	v_pk_fma_f32 v[44:45], s[20:21], v[52:53], v[44:45] op_sel_hi:[0,1,1]
	v_cvt_scalef32_pk_f32_fp4 v[52:53], v177, 1.0 op_sel:[1,0,0]
	v_pk_fma_f32 v[48:49], s[22:23], v[48:49], v[178:179] op_sel_hi:[0,1,1]
	v_cvt_scalef32_pk_f32_fp4 v[50:51], v183, 1.0 op_sel:[1,1,0]
	v_pk_fma_f32 v[46:47], s[20:21], v[52:53], v[46:47] op_sel_hi:[0,1,1]
	v_cvt_scalef32_pk_f32_fp4 v[52:53], v177, 1.0 op_sel:[0,1,0]
	v_pk_fma_f32 v[50:51], s[22:23], v[50:51], v[180:181] op_sel_hi:[0,1,1]
	v_pk_fma_f32 v[48:49], s[20:21], v[52:53], v[48:49] op_sel_hi:[0,1,1]
	v_cvt_scalef32_pk_f32_fp4 v[52:53], v177, 1.0 op_sel:[1,1,0]
	v_pk_fma_f32 v[50:51], s[20:21], v[52:53], v[50:51] op_sel_hi:[0,1,1]
	v_cvt_scalef32_pk_f32_fp4 v[52:53], v172, 1.0
	v_pk_fma_f32 v[36:37], s[18:19], v[52:53], v[36:37] op_sel_hi:[0,1,1]
	v_cvt_scalef32_pk_f32_fp4 v[52:53], v172, 1.0 op_sel:[1,0,0]
	v_pk_fma_f32 v[38:39], s[18:19], v[52:53], v[38:39] op_sel_hi:[0,1,1]
	v_cvt_scalef32_pk_f32_fp4 v[52:53], v172, 1.0 op_sel:[0,1,0]
	v_pk_fma_f32 v[40:41], s[18:19], v[52:53], v[40:41] op_sel_hi:[0,1,1]
	v_cvt_scalef32_pk_f32_fp4 v[52:53], v172, 1.0 op_sel:[1,1,0]
	v_pk_fma_f32 v[42:43], s[18:19], v[52:53], v[42:43] op_sel_hi:[0,1,1]
	v_cvt_scalef32_pk_f32_fp4 v[52:53], v173, 1.0
	v_pk_fma_f32 v[44:45], s[18:19], v[52:53], v[44:45] op_sel_hi:[0,1,1]
	v_cvt_scalef32_pk_f32_fp4 v[52:53], v173, 1.0 op_sel:[1,0,0]
	v_pk_fma_f32 v[46:47], s[18:19], v[52:53], v[46:47] op_sel_hi:[0,1,1]
	v_cvt_scalef32_pk_f32_fp4 v[52:53], v173, 1.0 op_sel:[0,1,0]
	v_pk_fma_f32 v[48:49], s[18:19], v[52:53], v[48:49] op_sel_hi:[0,1,1]
	v_cvt_scalef32_pk_f32_fp4 v[52:53], v173, 1.0 op_sel:[1,1,0]
	v_pk_fma_f32 v[50:51], s[18:19], v[52:53], v[50:51] op_sel_hi:[0,1,1]
	v_cvt_scalef32_pk_f32_fp4 v[52:53], v170, 1.0
	v_pk_fma_f32 v[36:37], s[6:7], v[52:53], v[36:37] op_sel_hi:[0,1,1]
	v_cvt_scalef32_pk_f32_fp4 v[52:53], v170, 1.0 op_sel:[1,0,0]
	v_pk_fma_f32 v[38:39], s[6:7], v[52:53], v[38:39] op_sel_hi:[0,1,1]
	v_cvt_scalef32_pk_f32_fp4 v[52:53], v170, 1.0 op_sel:[0,1,0]
	v_pk_fma_f32 v[40:41], s[6:7], v[52:53], v[40:41] op_sel_hi:[0,1,1]
	v_cvt_scalef32_pk_f32_fp4 v[52:53], v170, 1.0 op_sel:[1,1,0]
	v_pk_fma_f32 v[42:43], s[6:7], v[52:53], v[42:43] op_sel_hi:[0,1,1]
	v_cvt_scalef32_pk_f32_fp4 v[52:53], v171, 1.0
	v_pk_fma_f32 v[44:45], s[6:7], v[52:53], v[44:45] op_sel_hi:[0,1,1]
	v_cvt_scalef32_pk_f32_fp4 v[52:53], v171, 1.0 op_sel:[1,0,0]
	v_pk_fma_f32 v[46:47], s[6:7], v[52:53], v[46:47] op_sel_hi:[0,1,1]
	v_cvt_scalef32_pk_f32_fp4 v[52:53], v171, 1.0 op_sel:[0,1,0]
	v_pk_fma_f32 v[48:49], s[6:7], v[52:53], v[48:49] op_sel_hi:[0,1,1]
	v_cvt_scalef32_pk_f32_fp4 v[52:53], v171, 1.0 op_sel:[1,1,0]
	v_pk_fma_f32 v[50:51], s[6:7], v[52:53], v[50:51] op_sel_hi:[0,1,1]
	v_cvt_scalef32_pk_f32_fp4 v[52:53], v168, 1.0
	v_pk_fma_f32 v[36:37], s[30:31], v[52:53], v[36:37] op_sel_hi:[0,1,1]
	v_cvt_scalef32_pk_f32_fp4 v[52:53], v168, 1.0 op_sel:[1,0,0]
	v_pk_fma_f32 v[38:39], s[30:31], v[52:53], v[38:39] op_sel_hi:[0,1,1]
	v_cvt_scalef32_pk_f32_fp4 v[52:53], v168, 1.0 op_sel:[0,1,0]
	v_pk_fma_f32 v[40:41], s[30:31], v[52:53], v[40:41] op_sel_hi:[0,1,1]
	v_cvt_scalef32_pk_f32_fp4 v[52:53], v168, 1.0 op_sel:[1,1,0]
	v_pk_fma_f32 v[42:43], s[30:31], v[52:53], v[42:43] op_sel_hi:[0,1,1]
	v_cvt_scalef32_pk_f32_fp4 v[52:53], v169, 1.0
	v_pk_fma_f32 v[44:45], s[30:31], v[52:53], v[44:45] op_sel_hi:[0,1,1]
	v_cvt_scalef32_pk_f32_fp4 v[52:53], v169, 1.0 op_sel:[1,0,0]
	v_pk_fma_f32 v[46:47], s[30:31], v[52:53], v[46:47] op_sel_hi:[0,1,1]
	v_cvt_scalef32_pk_f32_fp4 v[52:53], v169, 1.0 op_sel:[0,1,0]
	v_pk_fma_f32 v[48:49], s[30:31], v[52:53], v[48:49] op_sel_hi:[0,1,1]
	v_cvt_scalef32_pk_f32_fp4 v[52:53], v169, 1.0 op_sel:[1,1,0]
	v_pk_fma_f32 v[50:51], s[30:31], v[52:53], v[50:51] op_sel_hi:[0,1,1]
	v_cvt_scalef32_pk_f32_fp4 v[52:53], v166, 1.0
	v_pk_fma_f32 v[36:37], s[28:29], v[52:53], v[36:37] op_sel_hi:[0,1,1]
	v_cvt_scalef32_pk_f32_fp4 v[52:53], v166, 1.0 op_sel:[1,0,0]
	v_pk_fma_f32 v[38:39], s[28:29], v[52:53], v[38:39] op_sel_hi:[0,1,1]
	v_cvt_scalef32_pk_f32_fp4 v[52:53], v166, 1.0 op_sel:[0,1,0]
	v_pk_fma_f32 v[40:41], s[28:29], v[52:53], v[40:41] op_sel_hi:[0,1,1]
	v_cvt_scalef32_pk_f32_fp4 v[52:53], v166, 1.0 op_sel:[1,1,0]
	v_pk_fma_f32 v[42:43], s[28:29], v[52:53], v[42:43] op_sel_hi:[0,1,1]
	v_cvt_scalef32_pk_f32_fp4 v[52:53], v167, 1.0
	v_pk_fma_f32 v[44:45], s[28:29], v[52:53], v[44:45] op_sel_hi:[0,1,1]
	v_cvt_scalef32_pk_f32_fp4 v[52:53], v167, 1.0 op_sel:[1,0,0]
	v_pk_fma_f32 v[46:47], s[28:29], v[52:53], v[46:47] op_sel_hi:[0,1,1]
	v_cvt_scalef32_pk_f32_fp4 v[52:53], v167, 1.0 op_sel:[0,1,0]
	v_pk_fma_f32 v[48:49], s[28:29], v[52:53], v[48:49] op_sel_hi:[0,1,1]
	v_cvt_scalef32_pk_f32_fp4 v[52:53], v167, 1.0 op_sel:[1,1,0]
	v_pk_fma_f32 v[50:51], s[28:29], v[52:53], v[50:51] op_sel_hi:[0,1,1]
	v_cvt_scalef32_pk_f32_fp4 v[52:53], v164, 1.0
	v_pk_fma_f32 v[36:37], s[26:27], v[52:53], v[36:37] op_sel_hi:[0,1,1]
	v_cvt_scalef32_pk_f32_fp4 v[52:53], v164, 1.0 op_sel:[1,0,0]
	v_pk_fma_f32 v[38:39], s[26:27], v[52:53], v[38:39] op_sel_hi:[0,1,1]
	v_cvt_scalef32_pk_f32_fp4 v[52:53], v164, 1.0 op_sel:[0,1,0]
	v_pk_fma_f32 v[40:41], s[26:27], v[52:53], v[40:41] op_sel_hi:[0,1,1]
	v_cvt_scalef32_pk_f32_fp4 v[52:53], v164, 1.0 op_sel:[1,1,0]
	v_pk_fma_f32 v[42:43], s[26:27], v[52:53], v[42:43] op_sel_hi:[0,1,1]
	v_cvt_scalef32_pk_f32_fp4 v[52:53], v165, 1.0
	v_pk_fma_f32 v[44:45], s[26:27], v[52:53], v[44:45] op_sel_hi:[0,1,1]
	v_cvt_scalef32_pk_f32_fp4 v[52:53], v165, 1.0 op_sel:[1,0,0]
	v_pk_fma_f32 v[46:47], s[26:27], v[52:53], v[46:47] op_sel_hi:[0,1,1]
	v_cvt_scalef32_pk_f32_fp4 v[52:53], v165, 1.0 op_sel:[0,1,0]
	v_pk_fma_f32 v[48:49], s[26:27], v[52:53], v[48:49] op_sel_hi:[0,1,1]
	v_cvt_scalef32_pk_f32_fp4 v[52:53], v165, 1.0 op_sel:[1,1,0]
	v_pk_fma_f32 v[50:51], s[26:27], v[52:53], v[50:51] op_sel_hi:[0,1,1]
	v_cvt_scalef32_pk_f32_fp4 v[52:53], v162, 1.0
	v_pk_fma_f32 v[36:37], s[24:25], v[52:53], v[36:37] op_sel_hi:[0,1,1]
	v_cvt_scalef32_pk_f32_fp4 v[52:53], v162, 1.0 op_sel:[1,0,0]
	v_pk_fma_f32 v[38:39], s[24:25], v[52:53], v[38:39] op_sel_hi:[0,1,1]
	v_cvt_scalef32_pk_f32_fp4 v[52:53], v162, 1.0 op_sel:[0,1,0]
	v_pk_fma_f32 v[40:41], s[24:25], v[52:53], v[40:41] op_sel_hi:[0,1,1]
	v_cvt_scalef32_pk_f32_fp4 v[52:53], v162, 1.0 op_sel:[1,1,0]
	v_pk_fma_f32 v[42:43], s[24:25], v[52:53], v[42:43] op_sel_hi:[0,1,1]
	v_cvt_scalef32_pk_f32_fp4 v[52:53], v163, 1.0
	v_pk_fma_f32 v[44:45], s[24:25], v[52:53], v[44:45] op_sel_hi:[0,1,1]
	v_cvt_scalef32_pk_f32_fp4 v[52:53], v163, 1.0 op_sel:[1,0,0]
	v_pk_fma_f32 v[46:47], s[24:25], v[52:53], v[46:47] op_sel_hi:[0,1,1]
	v_cvt_scalef32_pk_f32_fp4 v[52:53], v163, 1.0 op_sel:[0,1,0]
	v_pk_fma_f32 v[48:49], s[24:25], v[52:53], v[48:49] op_sel_hi:[0,1,1]
	v_cvt_scalef32_pk_f32_fp4 v[52:53], v163, 1.0 op_sel:[1,1,0]
	v_pk_fma_f32 v[50:51], s[24:25], v[52:53], v[50:51] op_sel_hi:[0,1,1]
	v_cvt_scalef32_pk_f32_fp4 v[52:53], v160, 1.0
	v_pk_fma_f32 v[36:37], s[40:41], v[52:53], v[36:37] op_sel_hi:[0,1,1]
	v_cvt_scalef32_pk_f32_fp4 v[52:53], v160, 1.0 op_sel:[1,0,0]
	v_pk_fma_f32 v[38:39], s[40:41], v[52:53], v[38:39] op_sel_hi:[0,1,1]
	v_cvt_scalef32_pk_f32_fp4 v[52:53], v160, 1.0 op_sel:[0,1,0]
	v_pk_fma_f32 v[40:41], s[40:41], v[52:53], v[40:41] op_sel_hi:[0,1,1]
	v_cvt_scalef32_pk_f32_fp4 v[52:53], v160, 1.0 op_sel:[1,1,0]
	v_pk_fma_f32 v[42:43], s[40:41], v[52:53], v[42:43] op_sel_hi:[0,1,1]
	v_cvt_scalef32_pk_f32_fp4 v[52:53], v161, 1.0
	v_pk_fma_f32 v[44:45], s[40:41], v[52:53], v[44:45] op_sel_hi:[0,1,1]
	v_cvt_scalef32_pk_f32_fp4 v[52:53], v161, 1.0 op_sel:[1,0,0]
	v_pk_fma_f32 v[46:47], s[40:41], v[52:53], v[46:47] op_sel_hi:[0,1,1]
	v_cvt_scalef32_pk_f32_fp4 v[52:53], v161, 1.0 op_sel:[0,1,0]
	v_pk_fma_f32 v[48:49], s[40:41], v[52:53], v[48:49] op_sel_hi:[0,1,1]
	v_cvt_scalef32_pk_f32_fp4 v[52:53], v161, 1.0 op_sel:[1,1,0]
	v_pk_fma_f32 v[50:51], s[40:41], v[52:53], v[50:51] op_sel_hi:[0,1,1]
	v_cvt_scalef32_pk_f32_fp4 v[52:53], v158, 1.0
	v_pk_fma_f32 v[36:37], s[38:39], v[52:53], v[36:37] op_sel_hi:[0,1,1]
	v_cvt_scalef32_pk_f32_fp4 v[52:53], v158, 1.0 op_sel:[1,0,0]
	v_pk_fma_f32 v[38:39], s[38:39], v[52:53], v[38:39] op_sel_hi:[0,1,1]
	v_cvt_scalef32_pk_f32_fp4 v[52:53], v158, 1.0 op_sel:[0,1,0]
	v_pk_fma_f32 v[40:41], s[38:39], v[52:53], v[40:41] op_sel_hi:[0,1,1]
	v_cvt_scalef32_pk_f32_fp4 v[52:53], v158, 1.0 op_sel:[1,1,0]
	v_pk_fma_f32 v[42:43], s[38:39], v[52:53], v[42:43] op_sel_hi:[0,1,1]
	v_cvt_scalef32_pk_f32_fp4 v[52:53], v159, 1.0
	v_pk_fma_f32 v[44:45], s[38:39], v[52:53], v[44:45] op_sel_hi:[0,1,1]
	v_cvt_scalef32_pk_f32_fp4 v[52:53], v159, 1.0 op_sel:[1,0,0]
	v_pk_fma_f32 v[46:47], s[38:39], v[52:53], v[46:47] op_sel_hi:[0,1,1]
	v_cvt_scalef32_pk_f32_fp4 v[52:53], v159, 1.0 op_sel:[0,1,0]
	v_pk_fma_f32 v[48:49], s[38:39], v[52:53], v[48:49] op_sel_hi:[0,1,1]
	v_cvt_scalef32_pk_f32_fp4 v[52:53], v159, 1.0 op_sel:[1,1,0]
	v_pk_fma_f32 v[50:51], s[38:39], v[52:53], v[50:51] op_sel_hi:[0,1,1]
	v_cvt_scalef32_pk_f32_fp4 v[52:53], v156, 1.0
	v_pk_fma_f32 v[36:37], s[36:37], v[52:53], v[36:37] op_sel_hi:[0,1,1]
	v_cvt_scalef32_pk_f32_fp4 v[52:53], v156, 1.0 op_sel:[1,0,0]
	v_pk_fma_f32 v[38:39], s[36:37], v[52:53], v[38:39] op_sel_hi:[0,1,1]
	v_cvt_scalef32_pk_f32_fp4 v[52:53], v156, 1.0 op_sel:[0,1,0]
	v_pk_fma_f32 v[40:41], s[36:37], v[52:53], v[40:41] op_sel_hi:[0,1,1]
	v_cvt_scalef32_pk_f32_fp4 v[52:53], v156, 1.0 op_sel:[1,1,0]
	v_pk_fma_f32 v[42:43], s[36:37], v[52:53], v[42:43] op_sel_hi:[0,1,1]
	v_cvt_scalef32_pk_f32_fp4 v[52:53], v157, 1.0
	v_pk_fma_f32 v[44:45], s[36:37], v[52:53], v[44:45] op_sel_hi:[0,1,1]
	v_cvt_scalef32_pk_f32_fp4 v[52:53], v157, 1.0 op_sel:[1,0,0]
	v_pk_fma_f32 v[46:47], s[36:37], v[52:53], v[46:47] op_sel_hi:[0,1,1]
	v_cvt_scalef32_pk_f32_fp4 v[52:53], v157, 1.0 op_sel:[0,1,0]
	v_pk_fma_f32 v[48:49], s[36:37], v[52:53], v[48:49] op_sel_hi:[0,1,1]
	v_cvt_scalef32_pk_f32_fp4 v[52:53], v157, 1.0 op_sel:[1,1,0]
	v_pk_fma_f32 v[50:51], s[36:37], v[52:53], v[50:51] op_sel_hi:[0,1,1]
	v_cvt_scalef32_pk_f32_fp4 v[52:53], v154, 1.0
	v_pk_fma_f32 v[36:37], s[34:35], v[52:53], v[36:37] op_sel_hi:[0,1,1]
	v_cvt_scalef32_pk_f32_fp4 v[52:53], v154, 1.0 op_sel:[1,0,0]
	v_pk_fma_f32 v[38:39], s[34:35], v[52:53], v[38:39] op_sel_hi:[0,1,1]
	v_cvt_scalef32_pk_f32_fp4 v[52:53], v154, 1.0 op_sel:[0,1,0]
	v_pk_fma_f32 v[40:41], s[34:35], v[52:53], v[40:41] op_sel_hi:[0,1,1]
	v_cvt_scalef32_pk_f32_fp4 v[52:53], v154, 1.0 op_sel:[1,1,0]
	v_pk_fma_f32 v[42:43], s[34:35], v[52:53], v[42:43] op_sel_hi:[0,1,1]
	v_cvt_scalef32_pk_f32_fp4 v[52:53], v155, 1.0
	v_pk_fma_f32 v[44:45], s[34:35], v[52:53], v[44:45] op_sel_hi:[0,1,1]
	v_cvt_scalef32_pk_f32_fp4 v[52:53], v155, 1.0 op_sel:[1,0,0]
	v_pk_fma_f32 v[46:47], s[34:35], v[52:53], v[46:47] op_sel_hi:[0,1,1]
	v_cvt_scalef32_pk_f32_fp4 v[52:53], v155, 1.0 op_sel:[0,1,0]
	v_pk_fma_f32 v[48:49], s[34:35], v[52:53], v[48:49] op_sel_hi:[0,1,1]
	v_cvt_scalef32_pk_f32_fp4 v[52:53], v155, 1.0 op_sel:[1,1,0]
	v_pk_fma_f32 v[50:51], s[34:35], v[52:53], v[50:51] op_sel_hi:[0,1,1]
	v_mov_b32_e32 v35, s49
	v_mov_b32_e32 v52, s25
	v_cndmask_b32_e64 v35, v35, v52, s[4:5]
	v_mov_b32_e32 v52, s35
	v_bfi_b32 v33, s47, v34, v33
	v_cndmask_b32_e64 v35, v35, v52, s[2:3]
	v_mov_b32_e32 v52, s7
	v_mul_f32_e32 v32, 0.5, v32
	v_add_f32_e32 v33, 1.0, v33
	v_cndmask_b32_e64 v35, v35, v52, s[0:1]
	v_mul_f32_e32 v32, v32, v33
	v_mul_f32_e32 v32, v35, v32
	v_cvt_scalef32_pk_f32_fp4 v[34:35], v152, 1.0 op_sel:[1,0,0]
	v_readlane_b32 s6, v32, 0
	v_readlane_b32 s18, v32, 32
	v_readlane_b32 s20, v32, 16
	v_readlane_b32 s22, v32, 48
	v_cvt_scalef32_pk_f32_fp4 v[32:33], v152, 1.0
	v_pk_fma_f32 v[32:33], s[6:7], v[32:33], v[36:37] op_sel_hi:[0,1,1]
	v_cvt_scalef32_pk_f32_fp4 v[36:37], v152, 1.0 op_sel:[0,1,0]
	v_pk_fma_f32 v[36:37], s[6:7], v[36:37], v[40:41] op_sel_hi:[0,1,1]
	v_cvt_scalef32_pk_f32_fp4 v[40:41], v153, 1.0
	v_pk_fma_f32 v[40:41], s[6:7], v[40:41], v[44:45] op_sel_hi:[0,1,1]
	v_cvt_scalef32_pk_f32_fp4 v[44:45], v153, 1.0 op_sel:[0,1,0]
	v_pk_fma_f32 v[44:45], s[6:7], v[44:45], v[48:49] op_sel_hi:[0,1,1]
	v_cvt_scalef32_pk_f32_fp4 v[48:49], v150, 1.0
	v_pk_fma_f32 v[34:35], s[6:7], v[34:35], v[38:39] op_sel_hi:[0,1,1]
	v_pk_fma_f32 v[32:33], s[18:19], v[48:49], v[32:33] op_sel_hi:[0,1,1]
	v_cvt_scalef32_pk_f32_fp4 v[48:49], v150, 1.0 op_sel:[1,0,0]
	v_cvt_scalef32_pk_f32_fp4 v[38:39], v152, 1.0 op_sel:[1,1,0]
	v_pk_fma_f32 v[34:35], s[18:19], v[48:49], v[34:35] op_sel_hi:[0,1,1]
	v_cvt_scalef32_pk_f32_fp4 v[48:49], v150, 1.0 op_sel:[0,1,0]
	v_pk_fma_f32 v[38:39], s[6:7], v[38:39], v[42:43] op_sel_hi:[0,1,1]
	v_pk_fma_f32 v[36:37], s[18:19], v[48:49], v[36:37] op_sel_hi:[0,1,1]
	v_cvt_scalef32_pk_f32_fp4 v[48:49], v150, 1.0 op_sel:[1,1,0]
	v_cvt_scalef32_pk_f32_fp4 v[42:43], v153, 1.0 op_sel:[1,0,0]
	v_pk_fma_f32 v[38:39], s[18:19], v[48:49], v[38:39] op_sel_hi:[0,1,1]
	v_cvt_scalef32_pk_f32_fp4 v[48:49], v151, 1.0
	v_pk_fma_f32 v[42:43], s[6:7], v[42:43], v[46:47] op_sel_hi:[0,1,1]
	v_pk_fma_f32 v[40:41], s[18:19], v[48:49], v[40:41] op_sel_hi:[0,1,1]
	v_cvt_scalef32_pk_f32_fp4 v[48:49], v151, 1.0 op_sel:[1,0,0]
	v_cvt_scalef32_pk_f32_fp4 v[46:47], v153, 1.0 op_sel:[1,1,0]
	v_pk_fma_f32 v[42:43], s[18:19], v[48:49], v[42:43] op_sel_hi:[0,1,1]
	v_cvt_scalef32_pk_f32_fp4 v[48:49], v151, 1.0 op_sel:[0,1,0]
	v_pk_fma_f32 v[46:47], s[6:7], v[46:47], v[50:51] op_sel_hi:[0,1,1]
	v_pk_fma_f32 v[44:45], s[18:19], v[48:49], v[44:45] op_sel_hi:[0,1,1]
	v_cvt_scalef32_pk_f32_fp4 v[48:49], v151, 1.0 op_sel:[1,1,0]
	v_pk_fma_f32 v[46:47], s[18:19], v[48:49], v[46:47] op_sel_hi:[0,1,1]
	v_cvt_scalef32_pk_f32_fp4 v[48:49], v148, 1.0
	v_pk_fma_f32 v[32:33], s[20:21], v[48:49], v[32:33] op_sel_hi:[0,1,1]
	v_cvt_scalef32_pk_f32_fp4 v[48:49], v148, 1.0 op_sel:[1,0,0]
	v_pk_fma_f32 v[34:35], s[20:21], v[48:49], v[34:35] op_sel_hi:[0,1,1]
	v_cvt_scalef32_pk_f32_fp4 v[48:49], v148, 1.0 op_sel:[0,1,0]
	v_pk_fma_f32 v[36:37], s[20:21], v[48:49], v[36:37] op_sel_hi:[0,1,1]
	v_cvt_scalef32_pk_f32_fp4 v[48:49], v148, 1.0 op_sel:[1,1,0]
	v_pk_fma_f32 v[38:39], s[20:21], v[48:49], v[38:39] op_sel_hi:[0,1,1]
	v_cvt_scalef32_pk_f32_fp4 v[48:49], v149, 1.0
	v_pk_fma_f32 v[40:41], s[20:21], v[48:49], v[40:41] op_sel_hi:[0,1,1]
	v_cvt_scalef32_pk_f32_fp4 v[48:49], v149, 1.0 op_sel:[1,0,0]
	v_pk_fma_f32 v[42:43], s[20:21], v[48:49], v[42:43] op_sel_hi:[0,1,1]
	v_cvt_scalef32_pk_f32_fp4 v[48:49], v149, 1.0 op_sel:[0,1,0]
	v_pk_fma_f32 v[44:45], s[20:21], v[48:49], v[44:45] op_sel_hi:[0,1,1]
	v_cvt_scalef32_pk_f32_fp4 v[48:49], v149, 1.0 op_sel:[1,1,0]
	v_pk_fma_f32 v[46:47], s[20:21], v[48:49], v[46:47] op_sel_hi:[0,1,1]
	v_cvt_scalef32_pk_f32_fp4 v[48:49], v146, 1.0
	v_pk_fma_f32 v[174:175], s[22:23], v[48:49], v[32:33] op_sel_hi:[0,1,1]
	v_cvt_scalef32_pk_f32_fp4 v[32:33], v146, 1.0 op_sel:[1,0,0]
	v_pk_fma_f32 v[192:193], s[22:23], v[32:33], v[34:35] op_sel_hi:[0,1,1]
	v_cvt_scalef32_pk_f32_fp4 v[32:33], v146, 1.0 op_sel:[0,1,0]
	v_pk_fma_f32 v[188:189], s[22:23], v[32:33], v[36:37] op_sel_hi:[0,1,1]
	v_cvt_scalef32_pk_f32_fp4 v[32:33], v146, 1.0 op_sel:[1,1,0]
	v_pk_fma_f32 v[190:191], s[22:23], v[32:33], v[38:39] op_sel_hi:[0,1,1]
	v_cvt_scalef32_pk_f32_fp4 v[32:33], v147, 1.0
	v_pk_fma_f32 v[184:185], s[22:23], v[32:33], v[40:41] op_sel_hi:[0,1,1]
	v_cvt_scalef32_pk_f32_fp4 v[32:33], v147, 1.0 op_sel:[1,0,0]
	v_pk_fma_f32 v[186:187], s[22:23], v[32:33], v[42:43] op_sel_hi:[0,1,1]
	v_cvt_scalef32_pk_f32_fp4 v[32:33], v147, 1.0 op_sel:[0,1,0]
	v_pk_fma_f32 v[178:179], s[22:23], v[32:33], v[44:45] op_sel_hi:[0,1,1]
	v_cvt_scalef32_pk_f32_fp4 v[32:33], v147, 1.0 op_sel:[1,1,0]
	v_pk_fma_f32 v[180:181], s[22:23], v[32:33], v[46:47] op_sel_hi:[0,1,1]
	s_and_b64 vcc, exec, s[8:9]
	s_cbranch_vccnz .LBB0_2569
	s_mov_b32 s18, s48
	s_add_i32 s48, s18, 16
	s_cmpk_gt_u32 s18, 0x6f
	s_cselect_b64 s[8:9], -1, 0
	s_cmpk_lt_u32 s18, 0x70
	s_cselect_b64 vcc, -1, 0
	s_bitcmp0_b32 s48, 6
	s_cselect_b64 s[6:7], -1, 0
	v_cndmask_b32_e64 v104, v102, v100, s[6:7]
	v_cndmask_b32_e32 v104, v114, v104, vcc
	s_nop 0
	s_waitcnt vmcnt(28)
	v_accvgpr_read_b32 v183, a29
	v_accvgpr_read_b32 v177, a31
	v_accvgpr_read_b32 v95, a11
	v_mov_b64_e32 v[88:89], v[250:251]
	v_accvgpr_read_b32 v182, a28
	v_accvgpr_read_b32 v176, a30
	v_accvgpr_read_b32 v94, a10
	v_accvgpr_read_b32 v93, a9
	v_accvgpr_read_b32 v92, a8
	v_mov_b64_e32 v[90:91], v[252:253]
	s_add_i32 s22, s18, 16
	v_readlane_b32 s20, v104, s22
	s_nop 1
	v_mad_i64_i32 v[108:109], s[6:7], s20, v194, v[96:97]
	global_load_dwordx4 a[8:11], v[108:109], off
	v_mad_i64_i32 v[108:109], s[6:7], s20, v194, v[98:99]
	global_load_dwordx2 a[28:29], v[108:109], off
	s_add_i32 s22, s18, 17
	v_readlane_b32 s20, v104, s22
	s_nop 1
	v_mad_i64_i32 v[108:109], s[6:7], s20, v194, v[96:97]
	global_load_dwordx4 v[250:253], v[108:109], off
	v_mad_i64_i32 v[108:109], s[6:7], s20, v194, v[98:99]
	global_load_dwordx2 a[30:31], v[108:109], off
	s_waitcnt vmcnt(28)
	v_accvgpr_read_b32 v173, a33
	v_accvgpr_read_b32 v171, a35
	v_accvgpr_read_b32 v87, a3
	v_accvgpr_read_b32 v83, a7
	v_accvgpr_read_b32 v172, a32
	v_accvgpr_read_b32 v170, a34
	v_accvgpr_read_b32 v86, a2
	v_accvgpr_read_b32 v85, a1
	v_accvgpr_read_b32 v84, a0
	v_accvgpr_read_b32 v82, a6
	v_accvgpr_read_b32 v81, a5
	v_accvgpr_read_b32 v80, a4
	s_add_i32 s22, s18, 18
	v_readlane_b32 s20, v104, s22
	s_nop 1
	v_mad_i64_i32 v[108:109], s[6:7], s20, v194, v[96:97]
	global_load_dwordx4 a[0:3], v[108:109], off
	v_mad_i64_i32 v[108:109], s[6:7], s20, v194, v[98:99]
	global_load_dwordx2 a[32:33], v[108:109], off
	s_add_i32 s22, s18, 19
	v_readlane_b32 s20, v104, s22
	s_nop 1
	v_mad_i64_i32 v[108:109], s[6:7], s20, v194, v[96:97]
	global_load_dwordx4 a[4:7], v[108:109], off
	v_mad_i64_i32 v[108:109], s[6:7], s20, v194, v[98:99]
	global_load_dwordx2 a[34:35], v[108:109], off
	s_waitcnt vmcnt(28)
	v_accvgpr_read_b32 v169, a37
	v_accvgpr_read_b32 v167, a39
	v_mov_b64_e32 v[76:77], v[214:215]
	v_mov_b64_e32 v[72:73], v[218:219]
	v_accvgpr_read_b32 v168, a36
	v_accvgpr_read_b32 v166, a38
	v_mov_b64_e32 v[78:79], v[216:217]
	v_mov_b64_e32 v[74:75], v[220:221]
	s_add_i32 s22, s18, 20
	v_readlane_b32 s20, v104, s22
	s_nop 1
	v_mad_i64_i32 v[108:109], s[6:7], s20, v194, v[96:97]
	global_load_dwordx4 v[214:217], v[108:109], off
	v_mad_i64_i32 v[108:109], s[6:7], s20, v194, v[98:99]
	global_load_dwordx2 a[36:37], v[108:109], off
	s_add_i32 s22, s18, 21
	v_readlane_b32 s20, v104, s22
	s_nop 1
	v_mad_i64_i32 v[108:109], s[6:7], s20, v194, v[96:97]
	global_load_dwordx4 v[218:221], v[108:109], off
	v_mad_i64_i32 v[108:109], s[6:7], s20, v194, v[98:99]
	global_load_dwordx2 a[38:39], v[108:109], off
	s_waitcnt vmcnt(28)
	v_accvgpr_read_b32 v165, a41
	v_accvgpr_read_b32 v163, a43
	v_mov_b64_e32 v[68:69], v[222:223]
	v_mov_b64_e32 v[64:65], v[226:227]
	v_accvgpr_read_b32 v164, a40
	v_accvgpr_read_b32 v162, a42
	v_mov_b64_e32 v[70:71], v[224:225]
	v_mov_b64_e32 v[66:67], v[228:229]
	s_add_i32 s22, s18, 22
	v_readlane_b32 s20, v104, s22
	s_nop 1
	v_mad_i64_i32 v[108:109], s[6:7], s20, v194, v[96:97]
	global_load_dwordx4 v[222:225], v[108:109], off
	v_mad_i64_i32 v[108:109], s[6:7], s20, v194, v[98:99]
	global_load_dwordx2 a[40:41], v[108:109], off
	s_add_i32 s22, s18, 23
	v_readlane_b32 s20, v104, s22
	s_nop 1
	v_mad_i64_i32 v[108:109], s[6:7], s20, v194, v[96:97]
	global_load_dwordx4 v[226:229], v[108:109], off
	v_mad_i64_i32 v[108:109], s[6:7], s20, v194, v[98:99]
	global_load_dwordx2 a[42:43], v[108:109], off
	s_waitcnt vmcnt(28)
	v_accvgpr_read_b32 v161, a45
	v_accvgpr_read_b32 v159, a47
	v_mov_b64_e32 v[60:61], v[230:231]
	v_mov_b64_e32 v[56:57], v[234:235]
	v_accvgpr_read_b32 v160, a44
	v_accvgpr_read_b32 v158, a46
	v_mov_b64_e32 v[62:63], v[232:233]
	v_mov_b64_e32 v[58:59], v[236:237]
	s_add_i32 s22, s18, 24
	v_readlane_b32 s20, v104, s22
	s_nop 1
	v_mad_i64_i32 v[108:109], s[6:7], s20, v194, v[96:97]
	global_load_dwordx4 v[230:233], v[108:109], off
	v_mad_i64_i32 v[108:109], s[6:7], s20, v194, v[98:99]
	global_load_dwordx2 a[44:45], v[108:109], off
	s_add_i32 s22, s18, 25
	v_readlane_b32 s20, v104, s22
	s_nop 1
	v_mad_i64_i32 v[108:109], s[6:7], s20, v194, v[96:97]
	global_load_dwordx4 v[234:237], v[108:109], off
	v_mad_i64_i32 v[108:109], s[6:7], s20, v194, v[98:99]
	global_load_dwordx2 a[46:47], v[108:109], off
	s_waitcnt vmcnt(28)
	v_accvgpr_read_b32 v157, a49
	v_accvgpr_read_b32 v155, a51
	v_mov_b64_e32 v[52:53], v[238:239]
	v_mov_b64_e32 v[48:49], v[242:243]
	v_accvgpr_read_b32 v156, a48
	v_accvgpr_read_b32 v154, a50
	v_mov_b64_e32 v[54:55], v[240:241]
	v_mov_b64_e32 v[50:51], v[244:245]
	s_add_i32 s22, s18, 26
	v_readlane_b32 s20, v104, s22
	s_nop 1
	v_mad_i64_i32 v[108:109], s[6:7], s20, v194, v[96:97]
	global_load_dwordx4 v[238:241], v[108:109], off
	v_mad_i64_i32 v[108:109], s[6:7], s20, v194, v[98:99]
	global_load_dwordx2 a[48:49], v[108:109], off
	s_add_i32 s22, s18, 27
	v_readlane_b32 s20, v104, s22
	s_nop 1
	v_mad_i64_i32 v[108:109], s[6:7], s20, v194, v[96:97]
	global_load_dwordx4 v[242:245], v[108:109], off
	v_mad_i64_i32 v[108:109], s[6:7], s20, v194, v[98:99]
	global_load_dwordx2 a[50:51], v[108:109], off
	s_waitcnt vmcnt(28)
	v_accvgpr_read_b32 v153, a25
	v_accvgpr_read_b32 v151, a23
	v_mov_b64_e32 v[44:45], v[246:247]
	v_mov_b64_e32 v[40:41], v[210:211]
	v_accvgpr_read_b32 v152, a24
	v_accvgpr_read_b32 v150, a22
	v_mov_b64_e32 v[46:47], v[248:249]
	v_mov_b64_e32 v[42:43], v[212:213]
	s_add_i32 s22, s18, 28
	v_readlane_b32 s20, v104, s22
	s_nop 1
	v_mad_i64_i32 v[108:109], s[6:7], s20, v194, v[96:97]
	global_load_dwordx4 v[246:249], v[108:109], off
	v_mad_i64_i32 v[108:109], s[6:7], s20, v194, v[98:99]
	global_load_dwordx2 a[24:25], v[108:109], off
	s_add_i32 s22, s18, 29
	v_readlane_b32 s20, v104, s22
	s_nop 1
	v_mad_i64_i32 v[108:109], s[6:7], s20, v194, v[96:97]
	global_load_dwordx4 v[210:213], v[108:109], off
	v_mad_i64_i32 v[108:109], s[6:7], s20, v194, v[98:99]
	global_load_dwordx2 a[22:23], v[108:109], off
	s_waitcnt vmcnt(28)
	v_accvgpr_read_b32 v149, a21
	v_accvgpr_read_b32 v147, a27
	v_mov_b64_e32 v[36:37], v[206:207]
	v_mov_b64_e32 v[32:33], v[202:203]
	v_accvgpr_read_b32 v148, a20
	v_accvgpr_read_b32 v146, a26
	v_mov_b64_e32 v[38:39], v[208:209]
	v_mov_b64_e32 v[34:35], v[204:205]
	s_add_i32 s22, s18, 30
	v_readlane_b32 s20, v104, s22
	s_nop 1
	v_mad_i64_i32 v[108:109], s[6:7], s20, v194, v[96:97]
	global_load_dwordx4 v[206:209], v[108:109], off
	v_mad_i64_i32 v[108:109], s[6:7], s20, v194, v[98:99]
	global_load_dwordx2 a[20:21], v[108:109], off
	s_add_i32 s22, s18, 31
	v_readlane_b32 s20, v104, s22
	s_nop 1
	v_mad_i64_i32 v[108:109], s[6:7], s20, v194, v[96:97]
	global_load_dwordx4 v[202:205], v[108:109], off
	v_mad_i64_i32 v[108:109], s[6:7], s20, v194, v[98:99]
	global_load_dwordx2 a[26:27], v[108:109], off
	s_cmp_lg_u32 s18, 64
	s_cbranch_scc1 .LBB0_2573
	global_load_dword a53, v[144:145], off
	global_load_dword a54, v[142:143], off
	global_load_dword v103, v[140:141], off
	global_load_dword v101, v[138:139], off
	s_branch .LBB0_2573
